# speedup vs baseline: 1.0181x; 1.0103x over previous
;     __device__ __forceinline__ void operator()(const f32x4 (&acc)[2][2][4][2], const Unit& u, int wr, int wc, int fr, int fq) const {
;     ...
;         float rqv[2][4];
; #pragma unroll
;         for (int ai = 0; ai < 2; ++ai)
; #pragma unroll
;             for (int m = 0; m < 4; ++m) rqv[ai][m] = rstd[row0 + ai * HALF + m * 16];
; #pragma unroll
;         for (int ai = 0; ai < 2; ++ai) {
;             f32x4 cs[4][4];
;             if (sect < 2) {
; #pragma unroll
;                 for (int m = 0; m < 4; ++m) { const int row = row0 + ai * HALF + m * 16; const int pos = row < TP ? row : ((row - TP) & 2047);
;                     cs[m][0] = *(const f32x4*)(rc + (size_t)pos * 64 + i0); cs[m][1] = *(const f32x4*)(rc + (size_t)pos * 64 + i0 + 4);
;                     cs[m][2] = *(const f32x4*)(rs + (size_t)pos * 64 + i0); cs[m][3] = *(const f32x4*)(rs + (size_t)pos * 64 + i0 + 4); }
;             }
; #pragma unroll
;             for (int m = 0; m < 4; ++m) { const int row = row0 + ai * HALF + m * 16;
;                 bf16_t* rowp = base + (size_t)row * DM + colbase;
;                 const float rq = rqv[ai][m];
;                 f32x4 a0 = acc[ai][0][m][0] * rq, a1 = acc[ai][0][m][1] * rq, b0 = acc[ai][1][m][0] * rq, b1 = acc[ai][1][m][1] * rq;
;                 f32x4 y10, y11, y20, y21;
;                 if (sect < 2) { const f32x4 c0 = cs[m][0], c1 = cs[m][1], s0 = cs[m][2], s1 = cs[m][3];
;                     y10 = a0 * c0 - b0 * s0; y11 = a1 * c1 - b1 * s1; y20 = b0 * c0 + a0 * s0; y21 = b1 * c1 + a1 * s1;
;                 } else { y10 = a0; y11 = a1; y20 = b0; y21 = b1; }
.LBB0_585:
	v_cndmask_b32_e64 v214, 0, 1, s[18:19]
	s_waitcnt vmcnt(0)
	s_cmp_eq_u32 s16, 0
	s_cselect_b32 s1, 0x3e0293ee, 1.0
	v_mul_f32_e32 v0, s1, v0
	v_mul_f32_e32 v238, s1, v238
	v_mul_f32_e32 v234, s1, v234
	v_mul_f32_e32 v230, s1, v230
	v_mul_f32_e32 v224, s1, v224
	v_mul_f32_e32 v222, s1, v222
	v_mul_f32_e32 v220, s1, v220
	v_mul_f32_e32 v218, s1, v218
	v_pk_mul_f32 v[188:189], v[188:189], v[0:1] op_sel_hi:[1,0]
	v_pk_mul_f32 v[186:187], v[186:187], v[0:1] op_sel_hi:[1,0]
	v_pk_mul_f32 v[180:181], v[180:181], v[0:1] op_sel_hi:[1,0]
	v_pk_mul_f32 v[178:179], v[178:179], v[0:1] op_sel_hi:[1,0]
	v_pk_mul_f32 v[168:169], v[168:169], v[0:1] op_sel_hi:[1,0]
	v_pk_mul_f32 v[166:167], v[166:167], v[0:1] op_sel_hi:[1,0]
	v_pk_mul_f32 v[156:157], v[156:157], v[0:1] op_sel_hi:[1,0]
	v_cmp_ne_u32_e64 s[8:9], 1, v214
	s_andn2_b64 vcc, exec, s[18:19]
	v_pk_mul_f32 v[240:241], v[154:155], v[0:1] op_sel_hi:[1,0]
	s_cbranch_vccnz .LBB0_587
	v_pk_mul_f32 v[154:155], v[168:169], v[192:193]
	v_pk_mul_f32 v[214:215], v[166:167], v[190:191]
	v_pk_fma_f32 v[248:249], v[188:189], v[176:177], v[154:155] neg_lo:[0,0,1] neg_hi:[0,0,1]
	v_pk_mul_f32 v[154:155], v[156:157], v[184:185]
	v_pk_fma_f32 v[246:247], v[186:187], v[174:175], v[214:215] neg_lo:[0,0,1] neg_hi:[0,0,1]
	v_pk_mul_f32 v[214:215], v[240:241], v[182:183]
	v_pk_fma_f32 v[216:217], v[180:181], v[172:173], v[154:155] neg_lo:[0,0,1] neg_hi:[0,0,1]
	v_pk_mul_f32 v[154:155], v[168:169], v[176:177]
	v_pk_mul_f32 v[166:167], v[166:167], v[174:175]
	v_pk_fma_f32 v[214:215], v[178:179], v[170:171], v[214:215] neg_lo:[0,0,1] neg_hi:[0,0,1]
	v_pk_fma_f32 v[168:169], v[188:189], v[192:193], v[154:155]
	v_pk_fma_f32 v[166:167], v[186:187], v[190:191], v[166:167]
	v_pk_mul_f32 v[154:155], v[156:157], v[172:173]
	v_pk_mul_f32 v[186:187], v[240:241], v[170:171]
	v_pk_fma_f32 v[156:157], v[180:181], v[184:185], v[154:155]
	v_pk_fma_f32 v[240:241], v[178:179], v[182:183], v[186:187]
	v_mov_b64_e32 v[186:187], v[246:247]
	v_mov_b64_e32 v[178:179], v[214:215]
	v_mov_b64_e32 v[188:189], v[248:249]
	v_mov_b64_e32 v[180:181], v[216:217]

; #define LAS __attribute__((address_space(3)))
; __device__ __forceinline__ int opaque_tid() { int t; asm volatile("v_mov_b32 %0, %1" : "=v"(t) : "v"(threadIdx.x)); return t; }
; __device__ __forceinline__ int v_rd_base(int lane) { return ((lane & 3) << 3) | (((lane >> 2) & 3) << 6) | (((lane >> 4) & 1) << 5) | (((lane >> 5) & 1) << 8); }
; __device__ __forceinline__ void attn_body256(const bf16_t* __restrict__ Qb, const bf16_t* __restrict__ Kh, const bf16_t* __restrict__ Vh,
;                                              bf16_t* Ob, int seq, unsigned char* lds, float lam, int MODE, bf16_t* Ab, const float* wsub) {
;   const int tid = opaque_tid(), wid = __builtin_amdgcn_readfirstlane(tid >> 6), lane = tid & 63, r32 = lane & 31, hi = lane >> 5;
;   LAS unsigned char* ldsl = (LAS unsigned char*)lds;
;   float* ws = (float*)(lds + A2_WS) + wid * 64; float* li_l = ws; float* al_l = ws + 32;
;   unsigned koff[2], voff[4];
; #pragma unroll
;   for (int i = 0; i < 2; ++i) { const int o = i * 8192 + tid * 16; const int row = o >> 8; const int colB = (o & 255) ^ ((row & 7) << 4);
;     koff[i] = (unsigned)(row * LDK + (colB >> 1));
;     const int sub = o >> 9, kk = (sub >> 2) * 8 + ((o & 511) >> 6), c = (sub & 3) * 32 + (((o & 511) >> 1) & 31);
;     const int k = (kk & ~0xC) | ((kk & 4) << 1) | ((kk & 8) >> 1);
;     voff[i] = (unsigned)(k * LDK + c); voff[2 + i] = (unsigned)(k * LDK + 128 + c); }
;     ...
;   const int NT = seq / KVBLK;
;   A2_DMA(0, 0); A2_DMA(1, 1);
;   float m_reg = -1e30f, l_reg = 0; f32x16 o[8] = {}; bf16x8 qr[8];
;   const bf16_t* Qw = Qb + (long)(wid * QBLK + r32) * LDQ + hi * 8;
; #pragma unroll
;   for (int d0 = 0; d0 < 8; ++d0) qr[d0] = *reinterpret_cast<const bf16x8*>(Qw + d0 * 16);
;   const int vb0 = (int)(uintptr_t)lds + v_rd_base(lane);
;   asm volatile("s_waitcnt vmcnt(0)" ::: "memory"); __syncthreads();
.LBB0_669:
	s_and_b32 s2, s18, 1
	s_lshl_b64 s[10:11], s[62:63], 11
	s_lshl_b64 s[6:7], s[62:63], 12
	s_add_u32 s9, s96, s6
	s_addc_u32 s12, s97, s7
	s_lshl_b32 s16, s8, 8
	s_lshl_b32 s6, s2, 7
	s_or_b32 s6, s16, s6
	s_ashr_i32 s7, s6, 31
	s_lshl_b64 s[14:15], s[6:7], 1
	s_add_u32 s6, s9, s14
	s_addc_u32 s7, s12, s15
	s_lshl_b64 s[8:9], s[0:1], 1
	s_add_u32 s0, s60, s8
	s_addc_u32 s1, s53, s9
	s_add_u32 s12, s0, s14
	s_addc_u32 s13, s1, s15
	v_mov_b32 v16, v231
	v_lshrrev_b32_e32 v245, 7, v231
	v_lshlrev_b32_e32 v245, 3, v245
	v_bfe_u32 v244, v231, 1, 3
	v_add_u32_e32 v245, v245, v244
	v_lshlrev_b32_e32 v245, 11, v245
	v_bfe_u32 v244, v231, 4, 3
	v_lshl_add_u32 v245, v244, 4, v245
	v_and_b32_e32 v244, 1, v231
	v_lshl_add_u32 v245, v244, 3, v245
	v_lshrrev_b32_e32 v239, 4, v231
	v_and_b32_e32 v244, 15, v239
	v_and_b32_e32 v242, 15, v231
	v_xor_b32_e32 v242, v242, v244
	v_lshlrev_b32_e32 v242, 3, v242
	v_lshl_add_u32 v239, v239, 11, v242
	s_add_u32 s20, s61, s8
	v_lshlrev_b32_e32 v17, 4, v16
	v_add_u32_e32 v6, 0x2000, v17
	s_addc_u32 s21, s68, s9
	s_ashr_i32 s17, s16, 31
	v_ashrrev_i32_e32 v8, 8, v6
	s_lshl_b64 s[0:1], s[16:17], 1
	v_and_b32_e32 v3, 0xf0, v17
	v_lshlrev_b32_e32 v6, 4, v8
	s_movk_i32 s26, 0x70
	s_add_u32 s16, s20, s0
	v_lshrrev_b32_e32 v0, 1, v16
	v_ashrrev_i32_e32 v2, 4, v16
	v_bitop3_b32 v3, v6, v3, s26 bitop3:0x6c
	s_addc_u32 s17, s21, s1
	v_readfirstlane_b32 s20, v16
	v_and_b32_e32 v22, 8, v0
	v_and_b32_e32 v0, 0x70, v16
	s_movk_i32 s21, 0xf0
	v_lshrrev_b32_e32 v4, 1, v2
	v_lshrrev_b32_e32 v3, 1, v3
	s_ashr_i32 s23, s20, 6
	v_bfe_u32 v18, v16, 2, 2
	v_lshlrev_b32_e32 v20, 3, v16
	v_bitop3_b32 v0, v17, v0, s21 bitop3:0x6c
	v_and_b32_e32 v4, 4, v4
	v_lshl_or_b32 v6, v8, 11, v3
	v_add_u32_e32 v6, 0x10000, v239
	v_and_b32_e32 v3, 0x1ffff0, v8
	v_lshrrev_b32_e32 v8, 1, v8
	v_and_b32_e32 v19, 0x60, v16
	v_and_b32_e32 v21, 24, v20
	v_or_b32_e32 v7, v22, v18
	v_lshrrev_b32_e32 v0, 1, v0
	v_and_or_b32 v23, v2, -16, v4
	v_and_b32_e32 v8, 4, v8
	s_lshl_b32 s21, s23, 10
	v_or_b32_e32 v5, v21, v19
	v_lshl_or_b32 v0, v2, 11, v0
	v_mov_b32_e32 v0, v239
	v_or_b32_e32 v2, v7, v23
	v_or3_b32 v3, v3, v8, v7
	s_add_i32 s21, s21, 0
	v_lshl_or_b32 v2, v2, 11, v5
	v_mov_b32_e32 v2, v245
	v_lshlrev_b32_e32 v24, 11, v3
	s_add_i32 s22, s21, 0x10000
	v_lshlrev_b64 v[12:13], 1, v[0:1]
	v_mov_b32_e32 v3, v1
	v_or_b32_e32 v4, 0x80, v2
	v_lshl_add_u64 v[14:15], s[12:13], 0, v[12:13]
	s_mov_b32 m0, s22
	v_lshlrev_b64 v[2:3], 1, v[2:3]
	s_add_i32 s24, s21, 0x4000
	global_load_lds_dwordx4 v[14:15], off
	v_lshl_add_u64 v[14:15], s[16:17], 0, v[2:3]
	s_mov_b32 m0, s21
	s_mov_b64 s[30:31], 0x100
	v_mov_b32_e32 v7, v1
	s_and_b32 s20, s20, 0x3fffffc0
	v_or_b32_e32 v8, v24, v5
	v_add_u32_e32 v8, 0x10000, v245
	global_load_lds_dwordx4 v[14:15], off
	v_lshl_add_u64 v[14:15], v[14:15], 0, s[30:31]
	s_mov_b32 m0, s24
	v_lshlrev_b64 v[6:7], 1, v[6:7]
	v_mov_b32_e32 v9, v1
	s_lshl_b32 s20, s20, 2
	v_or_b32_e32 v10, 0x80, v8
	global_load_lds_dwordx4 v[14:15], off
	v_lshl_add_u64 v[14:15], s[12:13], 0, v[6:7]
	s_add_i32 m0, s21, 0x12000
	v_lshlrev_b64 v[8:9], 1, v[8:9]
	s_add_i32 s20, s20, 0
	global_load_lds_dwordx4 v[14:15], off
	v_lshl_add_u64 v[14:15], s[16:17], 0, v[8:9]
	s_add_i32 m0, s21, 0x2000
	s_add_i32 s20, s20, 0x18000
	global_load_lds_dwordx4 v[14:15], off
	s_add_i32 m0, s21, 0x6000
	s_add_u32 s12, s12, 0x40000
	s_addc_u32 s13, s13, 0
	v_lshl_add_u64 v[14:15], v[14:15], 0, s[30:31]
	s_add_u32 s16, s16, 0x40000
	global_load_lds_dwordx4 v[14:15], off
	s_addc_u32 s17, s17, 0
	s_add_i32 m0, s21, 0x14000
	s_add_i32 s24, s21, 0x8000
	v_lshl_add_u64 v[14:15], s[12:13], 0, v[12:13]
	v_mov_b32_e32 v5, v1
	s_add_i32 s25, s21, 0xc000
	global_load_lds_dwordx4 v[14:15], off
	v_lshl_add_u64 v[2:3], s[16:17], 0, v[2:3]
	s_mov_b32 m0, s24
	v_mov_b32_e32 v11, v1
	global_load_lds_dwordx4 v[2:3], off
	v_lshl_add_u64 v[2:3], v[4:5], 1, s[16:17]
	s_mov_b32 m0, s25
	v_and_b32_e32 v228, 31, v16
	global_load_lds_dwordx4 v[2:3], off
	v_lshl_add_u64 v[2:3], s[12:13], 0, v[6:7]
	s_add_i32 m0, s21, 0x16000
	s_lshl_b32 s12, s23, 5
	global_load_lds_dwordx4 v[2:3], off
	v_lshl_add_u64 v[2:3], s[16:17], 0, v[8:9]
	s_add_i32 m0, s21, 0xa000
	v_bfe_u32 v229, v16, 5, 1
	global_load_lds_dwordx4 v[2:3], off
	v_lshl_add_u64 v[2:3], v[10:11], 1, s[16:17]
	s_add_i32 m0, s21, 0xe000
	v_lshlrev_b32_e32 v0, 4, v229
	global_load_lds_dwordx4 v[2:3], off
	v_and_b32_e32 v2, 15, v231
	v_or_b32_e32 v2, s12, v2
	v_mov_b32_e32 v3, 0
	v_lshlrev_b64 v[2:3], 12, v[2:3]
	v_lshl_add_u64 v[2:3], s[6:7], 0, v[2:3]
	v_bfe_u32 v194, v231, 4, 2
	v_lshlrev_b32_e32 v194, 4, v194
	v_mov_b32_e32 v195, 0
	v_lshl_add_u64 v[2:3], v[2:3], 0, v[194:195]
	global_load_dwordx4 v[162:165], v[2:3], off
	global_load_dwordx4 v[166:169], v[2:3], off offset:64
	global_load_dwordx4 v[170:173], v[2:3], off offset:128
	global_load_dwordx4 v[174:177], v[2:3], off offset:192
	v_mov_b32_e32 v194, 0x10000
	v_lshl_add_u64 v[2:3], v[2:3], 0, v[194:195]
	global_load_dwordx4 v[178:181], v[2:3], off
	global_load_dwordx4 v[182:185], v[2:3], off offset:64
	global_load_dwordx4 v[186:189], v[2:3], off offset:128
	global_load_dwordx4 v[190:193], v[2:3], off offset:192
	v_and_b32_e32 v8, 0x70, v17
	s_movk_i32 s6, 0x60
	v_bitop3_b32 v236, v0, v8, s6 bitop3:0x36
	s_movk_i32 s6, 0x80
	v_bitop3_b32 v237, v0, v8, s6 bitop3:0x36
	s_movk_i32 s6, 0xa0
	v_bitop3_b32 v240, v0, v8, s6 bitop3:0x36
	s_movk_i32 s6, 0xc0
	s_cmp_lg_u32 0, -1
	v_and_b32_e32 v2, 63, v16
	v_lshlrev_b32_e32 v3, 1, v16
	v_and_b32_e32 v4, 0x118, v20
	v_bitop3_b32 v241, v0, v8, s6 bitop3:0x36
	s_movk_i32 s6, 0xe0
	s_cselect_b32 s16, 0, 0
	s_lshl_b32 s23, s19, 18
	v_and_b32_e32 v5, 0xc0, v17
	v_bitop3_b32 v247, v0, v8, s6 bitop3:0x36
	v_cmp_gt_u32_e64 s[6:7], 32, v2
	v_and_or_b32 v2, v3, 32, v4
	s_add_u32 s14, s8, s14
	v_add3_u32 v248, v5, s16, v2
	s_addc_u32 s15, s9, s15
	v_readlane_b32 s16, v254, 41
	s_add_u32 s14, s16, s14
	v_readlane_b32 s16, v254, 42
	s_addc_u32 s15, s16, s15
	s_add_u32 s8, s8, s0
	s_addc_u32 s9, s9, s1
	v_or3_b32 v2, v23, v22, v18
	v_lshlrev_b32_e32 v2, 11, v2
	s_add_u32 s8, s88, s8
	v_or3_b32 v2, v2, v19, v21
	v_mov_b32_e32 v2, v245
	v_mov_b32_e32 v3, v1
	s_addc_u32 s9, s89, s9
	s_waitcnt vmcnt(0)
; #define SBAR() __builtin_amdgcn_sched_barrier(0)
; __device__ __forceinline__ int v_rd_base(int lane) { return ((lane & 3) << 3) | (((lane >> 2) & 3) << 6) | (((lane >> 4) & 1) << 5) | (((lane >> 5) & 1) << 8); }
; __device__ __forceinline__ void attn_body256(const bf16_t* __restrict__ Qb, const bf16_t* __restrict__ Kh, const bf16_t* __restrict__ Vh,
;                                              bf16_t* Ob, int seq, unsigned char* lds, float lam, int MODE, bf16_t* Ab, const float* wsub) {
;     ...
;   const int NT = seq / KVBLK;
;   A2_DMA(0, 0); A2_DMA(1, 1);
;   float m_reg = -1e30f, l_reg = 0; f32x16 o[8] = {}; bf16x8 qr[8];
;   const bf16_t* Qw = Qb + (long)(wid * QBLK + r32) * LDQ + hi * 8;
; #pragma unroll
;   for (int d0 = 0; d0 < 8; ++d0) qr[d0] = *reinterpret_cast<const bf16x8*>(Qw + d0 * 16);
;   const int vb0 = (int)(uintptr_t)lds + v_rd_base(lane);
;   asm volatile("s_waitcnt vmcnt(0)" ::: "memory"); __syncthreads();
;   for (int j = 0; j < NT; ++j) {
;     const int b = j & 1;
;     f32x16 p0, p1; float mn, alpha; bf16x8 pa0, pa1, pa2, pa3;
;     SBAR(); qkt(p0, p1, (const bf16_t*)(lds + A2_KOFF + b * A2_KBUF), qr, r32, hi);
	v_bitop3_b32 v232, v0, v17, s26 bitop3:0x78
	v_lshl_add_u64 v[224:225], v[2:3], 1, s[8:9]
	v_or3_b32 v2, v24, v19, v21
	v_add_u32_e32 v2, 0x10000, v245
	v_mov_b32_e32 v16, v1
	v_mov_b32_e32 v17, v1
	v_bitop3_b32 v233, v0, v8, 32 bitop3:0x36
	v_bitop3_b32 v234, v0, v8, 64 bitop3:0x36
	v_lshl_add_u64 v[220:221], s[14:15], 0, v[12:13]
	v_lshl_add_u64 v[222:223], s[14:15], 0, v[6:7]
	v_lshl_add_u64 v[226:227], v[2:3], 1, s[8:9]
	v_mov_b32_e32 v2, v1
	v_mov_b32_e32 v4, v1
	v_mov_b32_e32 v5, v1
	v_mov_b32_e32 v6, v1
	v_mov_b32_e32 v7, v1
	v_mov_b32_e32 v8, v1
	v_mov_b32_e32 v9, v1
	v_mov_b32_e32 v10, v1
	v_mov_b32_e32 v12, v1
	v_mov_b32_e32 v13, v1
	v_mov_b32_e32 v14, v1
	v_mov_b32_e32 v15, v1
	v_mov_b64_e32 v[128:129], v[16:17]
	v_mov_b64_e32 v[112:113], v[16:17]
	v_mov_b64_e32 v[96:97], v[16:17]
	v_mov_b64_e32 v[80:81], v[16:17]
	v_mov_b64_e32 v[64:65], v[16:17]
	v_mov_b64_e32 v[48:49], v[16:17]
	v_mov_b64_e32 v[32:33], v[16:17]
	s_mov_b32 s13, 2
	v_lshlrev_b32_e32 v230, 8, v228
	v_lshl_add_u32 v238, v228, 2, s20
	v_mov_b32_e32 v250, 0
	v_mov_b32_e32 v249, 0xf149f2ca
	s_mov_b64 s[14:15], 0
	v_mov_b64_e32 v[126:127], v[14:15]
	v_mov_b64_e32 v[124:125], v[12:13]
	v_mov_b64_e32 v[122:123], v[10:11]
	v_mov_b64_e32 v[120:121], v[8:9]
	v_mov_b64_e32 v[118:119], v[6:7]
	v_mov_b64_e32 v[116:117], v[4:5]
	v_mov_b64_e32 v[114:115], v[2:3]
	v_mov_b64_e32 v[110:111], v[14:15]
	v_mov_b64_e32 v[108:109], v[12:13]
	v_mov_b64_e32 v[106:107], v[10:11]
	v_mov_b64_e32 v[104:105], v[8:9]
	v_mov_b64_e32 v[102:103], v[6:7]
	v_mov_b64_e32 v[100:101], v[4:5]
	v_mov_b64_e32 v[98:99], v[2:3]
	v_mov_b64_e32 v[94:95], v[14:15]
	v_mov_b64_e32 v[92:93], v[12:13]
	v_mov_b64_e32 v[90:91], v[10:11]
	v_mov_b64_e32 v[88:89], v[8:9]
	v_mov_b64_e32 v[86:87], v[6:7]
	v_mov_b64_e32 v[84:85], v[4:5]
	v_mov_b64_e32 v[82:83], v[2:3]
	v_mov_b64_e32 v[78:79], v[14:15]
	v_mov_b64_e32 v[76:77], v[12:13]
	v_mov_b64_e32 v[74:75], v[10:11]
	v_mov_b64_e32 v[72:73], v[8:9]
	v_mov_b64_e32 v[70:71], v[6:7]
	v_mov_b64_e32 v[68:69], v[4:5]
	v_mov_b64_e32 v[66:67], v[2:3]
	v_mov_b64_e32 v[62:63], v[14:15]
	v_mov_b64_e32 v[60:61], v[12:13]
	v_mov_b64_e32 v[58:59], v[10:11]
	v_mov_b64_e32 v[56:57], v[8:9]
	v_mov_b64_e32 v[54:55], v[6:7]
	v_mov_b64_e32 v[52:53], v[4:5]
	v_mov_b64_e32 v[50:51], v[2:3]
	v_mov_b64_e32 v[46:47], v[14:15]
	v_mov_b64_e32 v[44:45], v[12:13]
	v_mov_b64_e32 v[42:43], v[10:11]
	v_mov_b64_e32 v[40:41], v[8:9]
	v_mov_b64_e32 v[38:39], v[6:7]
	v_mov_b64_e32 v[36:37], v[4:5]
	v_mov_b64_e32 v[34:35], v[2:3]
	v_mov_b64_e32 v[30:31], v[14:15]
	v_mov_b64_e32 v[28:29], v[12:13]
	v_mov_b64_e32 v[26:27], v[10:11]
	v_mov_b64_e32 v[24:25], v[8:9]
	v_mov_b64_e32 v[22:23], v[6:7]
	v_mov_b64_e32 v[20:21], v[4:5]
	v_mov_b64_e32 v[18:19], v[2:3]
	v_and_b32_e32 v237, 15, v231
	v_bfe_u32 v240, v231, 4, 2
	v_add_u32_e32 v247, 0, v240
	v_xor_b32_e32 v247, v247, v237
	v_lshlrev_b32_e32 v247, 4, v247
	v_lshl_add_u32 v232, v237, 8, v247
	v_add_u32_e32 v247, 4, v240
	v_xor_b32_e32 v247, v247, v237
	v_lshlrev_b32_e32 v247, 4, v247
	v_lshl_add_u32 v233, v237, 8, v247
	v_add_u32_e32 v247, 8, v240
	v_xor_b32_e32 v247, v247, v237
	v_lshlrev_b32_e32 v247, 4, v247
	v_lshl_add_u32 v246, v237, 8, v247
	v_add_u32_e32 v247, 12, v240
	v_xor_b32_e32 v247, v247, v237
	v_lshlrev_b32_e32 v247, 4, v247
	v_lshl_add_u32 v249, v237, 8, v247
	v_and_b32_e32 v247, 1, v240
	v_lshlrev_b32_e32 v248, 7, v247
	v_lshrrev_b32_e32 v247, 1, v240
	v_lshl_add_u32 v248, v247, 11, v248
	v_bfe_u32 v247, v231, 2, 2
	v_lshl_add_u32 v248, v247, 5, v248
	v_and_b32_e32 v247, 3, v231
	v_lshl_add_u32 v248, v247, 3, v248
	v_mov_b32_e32 v250, 0
	v_mov_b32_e32 v234, 0
	v_mov_b32_e32 v236, 0
	v_mov_b32_e32 v237, 0
	v_mov_b32_e32 v238, 0
	v_mov_b32_e32 v239, 0
	v_mov_b32_e32 v240, 0
	v_mov_b32_e32 v241, 0
	v_mov_b32_e32 v242, 0
	v_mov_b32_e32 v243, 0
	s_movk_i32 s62, 0x7fff
	s_waitcnt vmcnt(0) lgkmcnt(0)
	s_barrier
	s_mov_b32 s98, 0
	s_mov_b32 s99, 0x8000
	s_mov_b32 s100, 0x19000
	s_cmpk_ge_u32 s21, 0x1000
	s_cbranch_scc1 .Lat_y_qk
	s_mov_b32 s9, 0x10000
	v_add_u32_e32 v230, s9, v232
	v_add_u32_e32 v247, s9, v233
	v_add_u32_e32 v228, s9, v246
	v_add_u32_e32 v245, s9, v249
	ds_read_b128 v[194:197], v230
	ds_read_b128 v[198:201], v230 offset:4096
	ds_read_b128 v[202:205], v230 offset:8192
	ds_read_b128 v[206:209], v230 offset:12288
	ds_read_b128 v[210:213], v247
	ds_read_b128 v[214:217], v247 offset:4096
; __device__ __forceinline__ void partialSM(f32x16& p0, f32x16& p1, float& m_reg, float& mn, float& alpha) {
;   constexpr float C = SCALE * 1.4426950408889634f;
;   float pmax = p0[0]; for (int r = 1; r < 16; ++r) pmax = fmaxf(pmax, p0[r]); for (int r = 0; r < 16; ++r) pmax = fmaxf(pmax, p1[r]);
;   { auto rr = __builtin_amdgcn_permlane32_swap(__float_as_uint(pmax), __float_as_uint(pmax), false, false);
;     pmax = fmaxf(__uint_as_float(rr[0]), __uint_as_float(rr[1])); }
;   if (__builtin_expect(__all(pmax - m_reg <= THR / SCALE), 1)) { mn = m_reg; alpha = 1.f; }
;   else { mn = fmaxf(m_reg, pmax); alpha = __builtin_amdgcn_exp2f((m_reg - mn) * C); m_reg = mn; }
;   float mnC = -mn * C;
;   for (int r = 0; r < 16; ++r) p0[r] = fmaf(p0[r], C, mnC); for (int r = 0; r < 16; ++r) p1[r] = fmaf(p1[r], C, mnC);
;   for (int r = 0; r < 16; ++r) p0[r] = __builtin_amdgcn_exp2f(p0[r]);
; }
; __device__ __forceinline__ void finishSM(f32x16& p0, f32x16& p1, float alpha, float& l_reg, bf16x8& pa0, bf16x8& pa1, bf16x8& pa2, bf16x8& pa3) {
;   for (int r = 0; r < 16; ++r) p1[r] = __builtin_amdgcn_exp2f(p1[r]);
;   float ps = 0; for (int r = 0; r < 16; ++r) ps += p0[r]; for (int r = 0; r < 16; ++r) ps += p1[r];
;   { auto rr = __builtin_amdgcn_permlane32_swap(__float_as_uint(ps), __float_as_uint(ps), false, false);
;     ps = __uint_as_float(rr[0]) + __uint_as_float(rr[1]); }
;   l_reg = l_reg * alpha + ps;
;     ...
;   PK4(p0, 0, pa0); PK4(p0, 8, pa1); PK4(p1, 0, pa2); PK4(p1, 8, pa3);
;     ...
; }
; __device__ __forceinline__ void qkt(f32x16& p0, f32x16& p1, const bf16_t* Ks, const bf16x8* qr, int r32, int hi) {
;   p0 = f32x16{}; p1 = f32x16{};
;   for (int d0 = 0; d0 < 8; ++d0) { int cb = (d0 * 16 + hi * 8) * 2;
;     bf16x8 b0 = *reinterpret_cast<const bf16x8*>((const char*)Ks + KSWZ(r32, cb));
;     bf16x8 b1 = *reinterpret_cast<const bf16x8*>((const char*)Ks + KSWZ(32 + r32, cb));
;     p0 = __builtin_amdgcn_mfma_f32_32x32x16_bf16(b0, qr[d0], p0, 0, 0, 0);
;     p1 = __builtin_amdgcn_mfma_f32_32x32x16_bf16(b1, qr[d0], p1, 0, 0, 0); }
; }
.Lat_x_top:
	s_add_i32 s8, s13, -2
	s_and_b32 s25, s8, 1
	s_lshl_b32 s24, s25, 14
	s_setprio 1
	s_waitcnt lgkmcnt(5)
	v_mfma_f32_16x16x32_bf16 v[130:133], v[194:197], v[162:165], v[236:239]
	v_mfma_f32_16x16x32_bf16 v[134:137], v[194:197], v[178:181], v[240:243]
	ds_read_b128 v[194:197], v247 offset:8192
	s_waitcnt lgkmcnt(5)
	v_mfma_f32_16x16x32_bf16 v[138:141], v[198:201], v[162:165], v[236:239]
	v_mfma_f32_16x16x32_bf16 v[142:145], v[198:201], v[178:181], v[240:243]
	ds_read_b128 v[198:201], v247 offset:12288
	s_waitcnt lgkmcnt(5)
	v_mfma_f32_16x16x32_bf16 v[146:149], v[202:205], v[162:165], v[236:239]
	v_mfma_f32_16x16x32_bf16 v[150:153], v[202:205], v[178:181], v[240:243]
	ds_read_b128 v[202:205], v228
	s_waitcnt lgkmcnt(5)
	v_mfma_f32_16x16x32_bf16 v[154:157], v[206:209], v[162:165], v[236:239]
	v_mfma_f32_16x16x32_bf16 v[158:161], v[206:209], v[178:181], v[240:243]
	ds_read_b128 v[206:209], v228 offset:4096
	s_waitcnt lgkmcnt(5)
	v_mfma_f32_16x16x32_bf16 v[130:133], v[210:213], v[166:169], v[130:133]
	v_mfma_f32_16x16x32_bf16 v[134:137], v[210:213], v[182:185], v[134:137]
	ds_read_b128 v[210:213], v228 offset:8192
	s_waitcnt lgkmcnt(5)
	v_mfma_f32_16x16x32_bf16 v[138:141], v[214:217], v[166:169], v[138:141]
	v_mfma_f32_16x16x32_bf16 v[142:145], v[214:217], v[182:185], v[142:145]
	ds_read_b128 v[214:217], v228 offset:12288
	s_waitcnt lgkmcnt(5)
	v_mfma_f32_16x16x32_bf16 v[146:149], v[194:197], v[166:169], v[146:149]
	v_mfma_f32_16x16x32_bf16 v[150:153], v[194:197], v[182:185], v[150:153]
	ds_read_b128 v[194:197], v245
	s_waitcnt lgkmcnt(5)
	v_mfma_f32_16x16x32_bf16 v[154:157], v[198:201], v[166:169], v[154:157]
	v_mfma_f32_16x16x32_bf16 v[158:161], v[198:201], v[182:185], v[158:161]
	ds_read_b128 v[198:201], v245 offset:4096
	s_waitcnt lgkmcnt(5)
	v_mfma_f32_16x16x32_bf16 v[130:133], v[202:205], v[170:173], v[130:133]
	v_mfma_f32_16x16x32_bf16 v[134:137], v[202:205], v[186:189], v[134:137]
	ds_read_b128 v[202:205], v245 offset:8192
	s_waitcnt lgkmcnt(5)
	v_mfma_f32_16x16x32_bf16 v[138:141], v[206:209], v[170:173], v[138:141]
	v_mfma_f32_16x16x32_bf16 v[142:145], v[206:209], v[186:189], v[142:145]
	ds_read_b128 v[206:209], v245 offset:12288
	s_waitcnt lgkmcnt(5)
	v_mfma_f32_16x16x32_bf16 v[146:149], v[210:213], v[170:173], v[146:149]
	v_mfma_f32_16x16x32_bf16 v[150:153], v[210:213], v[186:189], v[150:153]
	s_waitcnt lgkmcnt(4)
	v_mfma_f32_16x16x32_bf16 v[154:157], v[214:217], v[170:173], v[154:157]
	v_mfma_f32_16x16x32_bf16 v[158:161], v[214:217], v[186:189], v[158:161]
	s_waitcnt lgkmcnt(3)
	v_mfma_f32_16x16x32_bf16 v[130:133], v[194:197], v[174:177], v[130:133]
	v_mfma_f32_16x16x32_bf16 v[134:137], v[194:197], v[190:193], v[134:137]
	s_waitcnt lgkmcnt(2)
	v_mfma_f32_16x16x32_bf16 v[138:141], v[198:201], v[174:177], v[138:141]
	v_mfma_f32_16x16x32_bf16 v[142:145], v[198:201], v[190:193], v[142:145]
	s_waitcnt lgkmcnt(1)
	v_mfma_f32_16x16x32_bf16 v[146:149], v[202:205], v[174:177], v[146:149]
	v_mfma_f32_16x16x32_bf16 v[150:153], v[202:205], v[190:193], v[150:153]
	s_waitcnt lgkmcnt(0)
	v_mfma_f32_16x16x32_bf16 v[154:157], v[206:209], v[174:177], v[154:157]
	v_mfma_f32_16x16x32_bf16 v[158:161], v[206:209], v[190:193], v[158:161]
	s_setprio 0
	s_nop 6
	v_max3_f32 v194, v130, v131, v132
	v_max3_f32 v194, v194, v133, v138
	v_max3_f32 v194, v194, v139, v140
	v_max3_f32 v194, v194, v141, v146
	v_max3_f32 v194, v194, v147, v148
	v_max3_f32 v194, v194, v149, v154
	v_max3_f32 v194, v194, v155, v156
	v_max_f32_e32 v194, v194, v157
	v_max3_f32 v195, v134, v135, v136
	v_max3_f32 v195, v195, v137, v142
	v_max3_f32 v195, v195, v143, v144
	v_max3_f32 v195, v195, v145, v150
	v_max3_f32 v195, v195, v151, v152
	v_max3_f32 v195, v195, v153, v158
	v_max3_f32 v195, v195, v159, v160
	v_max_f32_e32 v195, v195, v161
	v_mov_b32_e32 v196, v194
	v_mov_b32_e32 v197, v195
	s_nop 1
	v_permlane32_swap_b32_e32 v194, v196
	v_permlane32_swap_b32_e32 v195, v197
	v_max_f32_e32 v194, v194, v196
	v_max_f32_e32 v195, v195, v197
	v_mov_b32_e32 v196, v194
	v_mov_b32_e32 v197, v195
	s_nop 1
	v_permlane16_swap_b32_e32 v194, v196
	v_permlane16_swap_b32_e32 v195, v197
	v_max_f32_e32 v194, v194, v196
	v_max_f32_e32 v195, v195, v197
	v_max_f32_e32 v196, v194, v195
	v_cmp_nge_f32_e32 vcc, 0x4138aa3b, v196
	s_cbranch_vccnz .Lat_x_rare
	s_cmp_lg_u32 s13, 2
	s_cbranch_scc1 .Lat_x_noresc
; __device__ __forceinline__ int crow(int r, int hi) { return (r & 3) + 8 * (r >> 2) + 4 * hi; }
; __device__ __forceinline__ int crow(int r, int hi) { return (r & 3) + 8 * (r >> 2) + 4 * hi; }
; __device__ __forceinline__ void partialSM(f32x16& p0, f32x16& p1, float& m_reg, float& mn, float& alpha) {
;     ...
;   if (__builtin_expect(__all(pmax - m_reg <= THR / SCALE), 1)) { mn = m_reg; alpha = 1.f; }
;   else { mn = fmaxf(m_reg, pmax); alpha = __builtin_amdgcn_exp2f((m_reg - mn) * C); m_reg = mn; }
;   float mnC = -mn * C;
;   for (int r = 0; r < 16; ++r) p0[r] = fmaf(p0[r], C, mnC); for (int r = 0; r < 16; ++r) p1[r] = fmaf(p1[r], C, mnC);
; __device__ __forceinline__ void attn_body256(const bf16_t* __restrict__ Qb, const bf16_t* __restrict__ Kh, const bf16_t* __restrict__ Vh,
;                                              bf16_t* Ob, int seq, unsigned char* lds, float lam, int MODE, bf16_t* Ab, const float* wsub) {
;     ...
;     if (__any(alpha < 1.f)) { if (hi == 0) al_l[r32] = alpha; asm volatile("s_waitcnt lgkmcnt(0)" ::: "memory");
; #pragma unroll
;       for (int r = 0; r < 16; ++r) { const float a = al_l[crow(r, hi)];
; #pragma unroll
;         for (int d = 0; d < 8; ++d) o[d][r] *= a; } }
.Lat_x_rare:
	s_cmp_eq_u32 s13, 2
	s_cselect_b32 s8, 0xff7fffff, 0
	v_max_f32_e32 v200, s8, v194
	v_max_f32_e32 v201, s8, v195
	v_max_f32_e32 v196, 0, v200
	v_max_f32_e32 v198, 0, v201
	v_exp_f32_e64 v196, -v196
	v_exp_f32_e64 v198, -v198
	v_sub_f32_e32 v236, v236, v200
	v_sub_f32_e32 v237, v237, v200
	v_sub_f32_e32 v238, v238, v200
	v_sub_f32_e32 v239, v239, v200
	v_sub_f32_e32 v240, v240, v201
	v_sub_f32_e32 v241, v241, v201
	v_sub_f32_e32 v242, v242, v201
	v_sub_f32_e32 v243, v243, v201
	v_sub_f32_e32 v130, v130, v200
	v_sub_f32_e32 v131, v131, v200
	v_sub_f32_e32 v132, v132, v200
	v_sub_f32_e32 v133, v133, v200
	v_sub_f32_e32 v134, v134, v201
	v_sub_f32_e32 v135, v135, v201
	v_sub_f32_e32 v136, v136, v201
	v_sub_f32_e32 v137, v137, v201
	v_sub_f32_e32 v138, v138, v200
	v_sub_f32_e32 v139, v139, v200
	v_sub_f32_e32 v140, v140, v200
	v_sub_f32_e32 v141, v141, v200
	v_sub_f32_e32 v142, v142, v201
	v_sub_f32_e32 v143, v143, v201
	v_sub_f32_e32 v144, v144, v201
	v_sub_f32_e32 v145, v145, v201
	v_sub_f32_e32 v146, v146, v200
	v_sub_f32_e32 v147, v147, v200
	v_sub_f32_e32 v148, v148, v200
	v_sub_f32_e32 v149, v149, v200
	v_sub_f32_e32 v150, v150, v201
	v_sub_f32_e32 v151, v151, v201
	v_sub_f32_e32 v152, v152, v201
	v_sub_f32_e32 v153, v153, v201
	v_sub_f32_e32 v154, v154, v200
	v_sub_f32_e32 v155, v155, v200
	v_sub_f32_e32 v156, v156, v200
	v_sub_f32_e32 v157, v157, v200
	v_sub_f32_e32 v158, v158, v201
	v_sub_f32_e32 v159, v159, v201
	v_sub_f32_e32 v160, v160, v201
	v_sub_f32_e32 v161, v161, v201
	v_mul_f32_e32 v250, v250, v196
	v_mul_f32_e32 v234, v234, v198
	v_pk_mul_f32 v[2:3], v[2:3], v[196:197] op_sel_hi:[1,0]
	v_pk_mul_f32 v[4:5], v[4:5], v[196:197] op_sel_hi:[1,0]
	v_pk_mul_f32 v[6:7], v[6:7], v[198:199] op_sel_hi:[1,0]
	v_pk_mul_f32 v[8:9], v[8:9], v[198:199] op_sel_hi:[1,0]
	v_pk_mul_f32 v[10:11], v[10:11], v[196:197] op_sel_hi:[1,0]
	v_pk_mul_f32 v[12:13], v[12:13], v[196:197] op_sel_hi:[1,0]
	v_pk_mul_f32 v[14:15], v[14:15], v[198:199] op_sel_hi:[1,0]
	v_pk_mul_f32 v[16:17], v[16:17], v[198:199] op_sel_hi:[1,0]
	v_pk_mul_f32 v[114:115], v[114:115], v[196:197] op_sel_hi:[1,0]
	v_pk_mul_f32 v[116:117], v[116:117], v[196:197] op_sel_hi:[1,0]
	v_pk_mul_f32 v[118:119], v[118:119], v[198:199] op_sel_hi:[1,0]
	v_pk_mul_f32 v[120:121], v[120:121], v[198:199] op_sel_hi:[1,0]
	v_pk_mul_f32 v[122:123], v[122:123], v[196:197] op_sel_hi:[1,0]
	v_pk_mul_f32 v[124:125], v[124:125], v[196:197] op_sel_hi:[1,0]
	v_pk_mul_f32 v[126:127], v[126:127], v[198:199] op_sel_hi:[1,0]
	v_pk_mul_f32 v[128:129], v[128:129], v[198:199] op_sel_hi:[1,0]
	v_pk_mul_f32 v[98:99], v[98:99], v[196:197] op_sel_hi:[1,0]
	v_pk_mul_f32 v[100:101], v[100:101], v[196:197] op_sel_hi:[1,0]
	v_pk_mul_f32 v[102:103], v[102:103], v[198:199] op_sel_hi:[1,0]
	v_pk_mul_f32 v[104:105], v[104:105], v[198:199] op_sel_hi:[1,0]
	v_pk_mul_f32 v[106:107], v[106:107], v[196:197] op_sel_hi:[1,0]
	v_pk_mul_f32 v[108:109], v[108:109], v[196:197] op_sel_hi:[1,0]
	v_pk_mul_f32 v[110:111], v[110:111], v[198:199] op_sel_hi:[1,0]
	v_pk_mul_f32 v[112:113], v[112:113], v[198:199] op_sel_hi:[1,0]
	v_pk_mul_f32 v[82:83], v[82:83], v[196:197] op_sel_hi:[1,0]
	v_pk_mul_f32 v[84:85], v[84:85], v[196:197] op_sel_hi:[1,0]
	v_pk_mul_f32 v[86:87], v[86:87], v[198:199] op_sel_hi:[1,0]
	v_pk_mul_f32 v[88:89], v[88:89], v[198:199] op_sel_hi:[1,0]
	v_pk_mul_f32 v[90:91], v[90:91], v[196:197] op_sel_hi:[1,0]
	v_pk_mul_f32 v[92:93], v[92:93], v[196:197] op_sel_hi:[1,0]
	v_pk_mul_f32 v[94:95], v[94:95], v[198:199] op_sel_hi:[1,0]
	v_pk_mul_f32 v[96:97], v[96:97], v[198:199] op_sel_hi:[1,0]
	v_pk_mul_f32 v[66:67], v[66:67], v[196:197] op_sel_hi:[1,0]
	v_pk_mul_f32 v[68:69], v[68:69], v[196:197] op_sel_hi:[1,0]
	v_pk_mul_f32 v[70:71], v[70:71], v[198:199] op_sel_hi:[1,0]
	v_pk_mul_f32 v[72:73], v[72:73], v[198:199] op_sel_hi:[1,0]
	v_pk_mul_f32 v[74:75], v[74:75], v[196:197] op_sel_hi:[1,0]
	v_pk_mul_f32 v[76:77], v[76:77], v[196:197] op_sel_hi:[1,0]
	v_pk_mul_f32 v[78:79], v[78:79], v[198:199] op_sel_hi:[1,0]
	v_pk_mul_f32 v[80:81], v[80:81], v[198:199] op_sel_hi:[1,0]
	v_pk_mul_f32 v[50:51], v[50:51], v[196:197] op_sel_hi:[1,0]
	v_pk_mul_f32 v[52:53], v[52:53], v[196:197] op_sel_hi:[1,0]
	v_pk_mul_f32 v[54:55], v[54:55], v[198:199] op_sel_hi:[1,0]
	v_pk_mul_f32 v[56:57], v[56:57], v[198:199] op_sel_hi:[1,0]
	v_pk_mul_f32 v[58:59], v[58:59], v[196:197] op_sel_hi:[1,0]
	v_pk_mul_f32 v[60:61], v[60:61], v[196:197] op_sel_hi:[1,0]
	v_pk_mul_f32 v[62:63], v[62:63], v[198:199] op_sel_hi:[1,0]
	v_pk_mul_f32 v[64:65], v[64:65], v[198:199] op_sel_hi:[1,0]
	v_pk_mul_f32 v[34:35], v[34:35], v[196:197] op_sel_hi:[1,0]
	v_pk_mul_f32 v[36:37], v[36:37], v[196:197] op_sel_hi:[1,0]
	v_pk_mul_f32 v[38:39], v[38:39], v[198:199] op_sel_hi:[1,0]
	v_pk_mul_f32 v[40:41], v[40:41], v[198:199] op_sel_hi:[1,0]
	v_pk_mul_f32 v[42:43], v[42:43], v[196:197] op_sel_hi:[1,0]
	v_pk_mul_f32 v[44:45], v[44:45], v[196:197] op_sel_hi:[1,0]
	v_pk_mul_f32 v[46:47], v[46:47], v[198:199] op_sel_hi:[1,0]
	v_pk_mul_f32 v[48:49], v[48:49], v[198:199] op_sel_hi:[1,0]
	v_pk_mul_f32 v[18:19], v[18:19], v[196:197] op_sel_hi:[1,0]
	v_pk_mul_f32 v[20:21], v[20:21], v[196:197] op_sel_hi:[1,0]
	v_pk_mul_f32 v[22:23], v[22:23], v[198:199] op_sel_hi:[1,0]
	v_pk_mul_f32 v[24:25], v[24:25], v[198:199] op_sel_hi:[1,0]
	v_pk_mul_f32 v[26:27], v[26:27], v[196:197] op_sel_hi:[1,0]
	v_pk_mul_f32 v[28:29], v[28:29], v[196:197] op_sel_hi:[1,0]
	v_pk_mul_f32 v[30:31], v[30:31], v[198:199] op_sel_hi:[1,0]
	v_pk_mul_f32 v[32:33], v[32:33], v[198:199] op_sel_hi:[1,0]
; #define SBAR() __builtin_amdgcn_sched_barrier(0)
; #define PV_STEP(B) do { pv_reads<(B) + 1>(fn, vb); asm volatile("s_waitcnt lgkmcnt(8)" ::: "memory"); SBAR(); pv_mma(o[B], fc, pa0, pa1, pa2, pa3); SBAR(); fc = fn; } while (0)
; __device__ __forceinline__ void partialSM(f32x16& p0, f32x16& p1, float& m_reg, float& mn, float& alpha) {
;     ...
;   for (int r = 0; r < 16; ++r) p0[r] = __builtin_amdgcn_exp2f(p0[r]);
; }
; __device__ __forceinline__ void finishSM(f32x16& p0, f32x16& p1, float alpha, float& l_reg, bf16x8& pa0, bf16x8& pa1, bf16x8& pa2, bf16x8& pa3) {
;   for (int r = 0; r < 16; ++r) p1[r] = __builtin_amdgcn_exp2f(p1[r]);
;   float ps = 0; for (int r = 0; r < 16; ++r) ps += p0[r]; for (int r = 0; r < 16; ++r) ps += p1[r];
;   { auto rr = __builtin_amdgcn_permlane32_swap(__float_as_uint(ps), __float_as_uint(ps), false, false);
;     ps = __uint_as_float(rr[0]) + __uint_as_float(rr[1]); }
;   l_reg = l_reg * alpha + ps;
;     ...
;   PK4(p0, 0, pa0); PK4(p0, 8, pa1); PK4(p1, 0, pa2); PK4(p1, 8, pa3);
; __device__ __forceinline__ void pv_all(f32x16* o, int vb, bf16x8 pa0, bf16x8 pa1, bf16x8 pa2, bf16x8 pa3) {
;   VFrag fc, fn;
;   pv_reads<0>(fc, vb);
;   PV_STEP(0); PV_STEP(1); PV_STEP(2); PV_STEP(3); PV_STEP(4); PV_STEP(5); PV_STEP(6);
;   asm volatile("s_waitcnt lgkmcnt(0)" ::: "memory"); SBAR(); pv_mma(o[7], fc, pa0, pa1, pa2, pa3);
; }
.Lat_x_noresc:
	v_exp_f32_e32 v130, v130
	v_exp_f32_e32 v131, v131
	v_exp_f32_e32 v132, v132
	v_exp_f32_e32 v133, v133
	v_exp_f32_e32 v134, v134
	v_exp_f32_e32 v135, v135
	v_exp_f32_e32 v136, v136
	v_exp_f32_e32 v137, v137
	v_exp_f32_e32 v138, v138
	v_exp_f32_e32 v139, v139
	v_exp_f32_e32 v140, v140
	v_exp_f32_e32 v141, v141
	v_exp_f32_e32 v142, v142
	v_exp_f32_e32 v143, v143
	v_exp_f32_e32 v144, v144
	v_exp_f32_e32 v145, v145
	v_exp_f32_e32 v146, v146
	v_exp_f32_e32 v147, v147
	v_exp_f32_e32 v148, v148
	v_exp_f32_e32 v149, v149
	v_exp_f32_e32 v150, v150
	v_exp_f32_e32 v151, v151
	v_exp_f32_e32 v152, v152
	v_exp_f32_e32 v153, v153
	v_exp_f32_e32 v154, v154
	v_exp_f32_e32 v155, v155
	v_exp_f32_e32 v156, v156
	v_exp_f32_e32 v157, v157
	v_exp_f32_e32 v158, v158
	v_exp_f32_e32 v159, v159
	v_exp_f32_e32 v160, v160
	v_exp_f32_e32 v161, v161
	v_add_f32_e32 v194, v130, v131
	v_add_f32_e32 v194, v194, v132
	v_add_f32_e32 v194, v194, v133
	v_add_f32_e32 v194, v194, v138
	v_add_f32_e32 v194, v194, v139
	v_add_f32_e32 v194, v194, v140
	v_add_f32_e32 v194, v194, v141
	v_add_f32_e32 v194, v194, v146
	v_add_f32_e32 v194, v194, v147
	v_add_f32_e32 v194, v194, v148
	v_add_f32_e32 v194, v194, v149
	v_add_f32_e32 v194, v194, v154
	v_add_f32_e32 v194, v194, v155
	v_add_f32_e32 v194, v194, v156
	v_add_f32_e32 v194, v194, v157
	v_add_f32_e32 v195, v134, v135
	v_add_f32_e32 v195, v195, v136
	v_add_f32_e32 v195, v195, v137
	v_add_f32_e32 v195, v195, v142
	v_add_f32_e32 v195, v195, v143
	v_add_f32_e32 v195, v195, v144
	v_add_f32_e32 v195, v195, v145
	v_add_f32_e32 v195, v195, v150
	v_add_f32_e32 v195, v195, v151
	v_add_f32_e32 v195, v195, v152
	v_add_f32_e32 v195, v195, v153
	v_add_f32_e32 v195, v195, v158
	v_add_f32_e32 v195, v195, v159
	v_add_f32_e32 v195, v195, v160
	v_add_f32_e32 v195, v195, v161
	v_add_f32_e32 v250, v250, v194
	v_add_f32_e32 v234, v234, v195
	v_cvt_pk_bf16_f32 v130, v130, v131
	v_cvt_pk_bf16_f32 v131, v132, v133
	v_cvt_pk_bf16_f32 v132, v138, v139
	v_cvt_pk_bf16_f32 v133, v140, v141
	v_cvt_pk_bf16_f32 v134, v134, v135
	v_cvt_pk_bf16_f32 v135, v136, v137
	v_cvt_pk_bf16_f32 v136, v142, v143
	v_cvt_pk_bf16_f32 v137, v144, v145
	v_cvt_pk_bf16_f32 v138, v146, v147
	v_cvt_pk_bf16_f32 v139, v148, v149
	v_cvt_pk_bf16_f32 v140, v154, v155
	v_cvt_pk_bf16_f32 v141, v156, v157
	v_cvt_pk_bf16_f32 v142, v150, v151
	v_cvt_pk_bf16_f32 v143, v152, v153
	v_cvt_pk_bf16_f32 v144, v158, v159
	v_cvt_pk_bf16_f32 v145, v160, v161
	v_add_u32_e32 v244, s98, v248
	ds_read_b64_tr_b16 v[146:147], v244
	ds_read_b64_tr_b16 v[148:149], v244 offset:4096
	ds_read_b64_tr_b16 v[150:151], v244 offset:8192
	ds_read_b64_tr_b16 v[152:153], v244 offset:12288
	ds_read_b64_tr_b16 v[154:155], v244 offset:256
	ds_read_b64_tr_b16 v[156:157], v244 offset:4352
	ds_read_b64_tr_b16 v[158:159], v244 offset:8448
	ds_read_b64_tr_b16 v[160:161], v244 offset:12544
	ds_read_b64_tr_b16 v[194:195], v244 offset:512
	ds_read_b64_tr_b16 v[196:197], v244 offset:4608
	ds_read_b64_tr_b16 v[198:199], v244 offset:8704
	ds_read_b64_tr_b16 v[200:201], v244 offset:12800
	s_waitcnt lgkmcnt(8)
	v_mfma_f32_16x16x32_bf16 v[2:5], v[146:149], v[130:133], v[2:5]
	v_mfma_f32_16x16x32_bf16 v[6:9], v[146:149], v[134:137], v[6:9]
	v_mfma_f32_16x16x32_bf16 v[2:5], v[150:153], v[138:141], v[2:5]
	v_mfma_f32_16x16x32_bf16 v[6:9], v[150:153], v[142:145], v[6:9]
	ds_read_b64_tr_b16 v[146:147], v244 offset:768
	ds_read_b64_tr_b16 v[148:149], v244 offset:4864
	ds_read_b64_tr_b16 v[150:151], v244 offset:8960
	ds_read_b64_tr_b16 v[152:153], v244 offset:13056
	s_waitcnt lgkmcnt(8)
	v_mfma_f32_16x16x32_bf16 v[10:13], v[154:157], v[130:133], v[10:13]
	v_mfma_f32_16x16x32_bf16 v[14:17], v[154:157], v[134:137], v[14:17]
	v_mfma_f32_16x16x32_bf16 v[10:13], v[158:161], v[138:141], v[10:13]
	v_mfma_f32_16x16x32_bf16 v[14:17], v[158:161], v[142:145], v[14:17]
	ds_read_b64_tr_b16 v[154:155], v244 offset:1024
	ds_read_b64_tr_b16 v[156:157], v244 offset:5120
	ds_read_b64_tr_b16 v[158:159], v244 offset:9216
	ds_read_b64_tr_b16 v[160:161], v244 offset:13312
	s_waitcnt lgkmcnt(8)
	v_mfma_f32_16x16x32_bf16 v[114:117], v[194:197], v[130:133], v[114:117]
	v_mfma_f32_16x16x32_bf16 v[118:121], v[194:197], v[134:137], v[118:121]
	v_mfma_f32_16x16x32_bf16 v[114:117], v[198:201], v[138:141], v[114:117]
	v_mfma_f32_16x16x32_bf16 v[118:121], v[198:201], v[142:145], v[118:121]
	ds_read_b64_tr_b16 v[194:195], v244 offset:1280
	ds_read_b64_tr_b16 v[196:197], v244 offset:5376
	ds_read_b64_tr_b16 v[198:199], v244 offset:9472
	ds_read_b64_tr_b16 v[200:201], v244 offset:13568
	s_waitcnt lgkmcnt(8)
	v_mfma_f32_16x16x32_bf16 v[122:125], v[146:149], v[130:133], v[122:125]
	v_mfma_f32_16x16x32_bf16 v[126:129], v[146:149], v[134:137], v[126:129]
	v_mfma_f32_16x16x32_bf16 v[122:125], v[150:153], v[138:141], v[122:125]
	v_mfma_f32_16x16x32_bf16 v[126:129], v[150:153], v[142:145], v[126:129]
	ds_read_b64_tr_b16 v[146:147], v244 offset:1536
	ds_read_b64_tr_b16 v[148:149], v244 offset:5632
	ds_read_b64_tr_b16 v[150:151], v244 offset:9728
	ds_read_b64_tr_b16 v[152:153], v244 offset:13824
	s_waitcnt lgkmcnt(8)
	v_mfma_f32_16x16x32_bf16 v[98:101], v[154:157], v[130:133], v[98:101]
	v_mfma_f32_16x16x32_bf16 v[102:105], v[154:157], v[134:137], v[102:105]
	v_mfma_f32_16x16x32_bf16 v[98:101], v[158:161], v[138:141], v[98:101]
	v_mfma_f32_16x16x32_bf16 v[102:105], v[158:161], v[142:145], v[102:105]
	ds_read_b64_tr_b16 v[154:155], v244 offset:1792
	ds_read_b64_tr_b16 v[156:157], v244 offset:5888
	ds_read_b64_tr_b16 v[158:159], v244 offset:9984
	ds_read_b64_tr_b16 v[160:161], v244 offset:14080
	s_waitcnt lgkmcnt(8)
; #define SBAR() __builtin_amdgcn_sched_barrier(0)
; #define PV_STEP(B) do { pv_reads<(B) + 1>(fn, vb); asm volatile("s_waitcnt lgkmcnt(8)" ::: "memory"); SBAR(); pv_mma(o[B], fc, pa0, pa1, pa2, pa3); SBAR(); fc = fn; } while (0)
; __device__ __forceinline__ void pv_all(f32x16* o, int vb, bf16x8 pa0, bf16x8 pa1, bf16x8 pa2, bf16x8 pa3) {
;   VFrag fc, fn;
;   pv_reads<0>(fc, vb);
;   PV_STEP(0); PV_STEP(1); PV_STEP(2); PV_STEP(3); PV_STEP(4); PV_STEP(5); PV_STEP(6);
;   asm volatile("s_waitcnt lgkmcnt(0)" ::: "memory"); SBAR(); pv_mma(o[7], fc, pa0, pa1, pa2, pa3);
; }
; __device__ __forceinline__ void attn_body256(const bf16_t* __restrict__ Qb, const bf16_t* __restrict__ Kh, const bf16_t* __restrict__ Vh,
;                                              bf16_t* Ob, int seq, unsigned char* lds, float lam, int MODE, bf16_t* Ab, const float* wsub) {
;     ...
;     pv_all(o, vb0 + b * A2_VBUF, pa0, pa1, pa2, pa3);
;     asm volatile("s_waitcnt vmcnt(0)" ::: "memory"); __syncthreads();
;     if (j + 2 < NT) A2_DMA(j + 2, b);
	v_mfma_f32_16x16x32_bf16 v[106:109], v[194:197], v[130:133], v[106:109]
	v_mfma_f32_16x16x32_bf16 v[110:113], v[194:197], v[134:137], v[110:113]
	v_mfma_f32_16x16x32_bf16 v[106:109], v[198:201], v[138:141], v[106:109]
	v_mfma_f32_16x16x32_bf16 v[110:113], v[198:201], v[142:145], v[110:113]
	ds_read_b64_tr_b16 v[194:195], v244 offset:16384
	ds_read_b64_tr_b16 v[196:197], v244 offset:20480
	ds_read_b64_tr_b16 v[198:199], v244 offset:24576
	ds_read_b64_tr_b16 v[200:201], v244 offset:28672
	s_waitcnt lgkmcnt(8)
	v_mfma_f32_16x16x32_bf16 v[82:85], v[146:149], v[130:133], v[82:85]
	v_mfma_f32_16x16x32_bf16 v[86:89], v[146:149], v[134:137], v[86:89]
	v_mfma_f32_16x16x32_bf16 v[82:85], v[150:153], v[138:141], v[82:85]
	v_mfma_f32_16x16x32_bf16 v[86:89], v[150:153], v[142:145], v[86:89]
	ds_read_b64_tr_b16 v[146:147], v244 offset:16640
	ds_read_b64_tr_b16 v[148:149], v244 offset:20736
	ds_read_b64_tr_b16 v[150:151], v244 offset:24832
	ds_read_b64_tr_b16 v[152:153], v244 offset:28928
	s_waitcnt lgkmcnt(8)
	v_mfma_f32_16x16x32_bf16 v[90:93], v[154:157], v[130:133], v[90:93]
	v_mfma_f32_16x16x32_bf16 v[94:97], v[154:157], v[134:137], v[94:97]
	v_mfma_f32_16x16x32_bf16 v[90:93], v[158:161], v[138:141], v[90:93]
	v_mfma_f32_16x16x32_bf16 v[94:97], v[158:161], v[142:145], v[94:97]
	ds_read_b64_tr_b16 v[154:155], v244 offset:16896
	ds_read_b64_tr_b16 v[156:157], v244 offset:20992
	ds_read_b64_tr_b16 v[158:159], v244 offset:25088
	ds_read_b64_tr_b16 v[160:161], v244 offset:29184
	s_waitcnt lgkmcnt(8)
	v_mfma_f32_16x16x32_bf16 v[66:69], v[194:197], v[130:133], v[66:69]
	v_mfma_f32_16x16x32_bf16 v[70:73], v[194:197], v[134:137], v[70:73]
	v_mfma_f32_16x16x32_bf16 v[66:69], v[198:201], v[138:141], v[66:69]
	v_mfma_f32_16x16x32_bf16 v[70:73], v[198:201], v[142:145], v[70:73]
	ds_read_b64_tr_b16 v[194:195], v244 offset:17152
	ds_read_b64_tr_b16 v[196:197], v244 offset:21248
	ds_read_b64_tr_b16 v[198:199], v244 offset:25344
	ds_read_b64_tr_b16 v[200:201], v244 offset:29440
	s_waitcnt lgkmcnt(8)
	v_mfma_f32_16x16x32_bf16 v[74:77], v[146:149], v[130:133], v[74:77]
	v_mfma_f32_16x16x32_bf16 v[78:81], v[146:149], v[134:137], v[78:81]
	v_mfma_f32_16x16x32_bf16 v[74:77], v[150:153], v[138:141], v[74:77]
	v_mfma_f32_16x16x32_bf16 v[78:81], v[150:153], v[142:145], v[78:81]
	ds_read_b64_tr_b16 v[146:147], v244 offset:17408
	ds_read_b64_tr_b16 v[148:149], v244 offset:21504
	ds_read_b64_tr_b16 v[150:151], v244 offset:25600
	ds_read_b64_tr_b16 v[152:153], v244 offset:29696
	s_waitcnt lgkmcnt(8)
	v_mfma_f32_16x16x32_bf16 v[50:53], v[154:157], v[130:133], v[50:53]
	v_mfma_f32_16x16x32_bf16 v[54:57], v[154:157], v[134:137], v[54:57]
	v_mfma_f32_16x16x32_bf16 v[50:53], v[158:161], v[138:141], v[50:53]
	v_mfma_f32_16x16x32_bf16 v[54:57], v[158:161], v[142:145], v[54:57]
	ds_read_b64_tr_b16 v[154:155], v244 offset:17664
	ds_read_b64_tr_b16 v[156:157], v244 offset:21760
	ds_read_b64_tr_b16 v[158:159], v244 offset:25856
	ds_read_b64_tr_b16 v[160:161], v244 offset:29952
	s_waitcnt lgkmcnt(8)
	v_mfma_f32_16x16x32_bf16 v[58:61], v[194:197], v[130:133], v[58:61]
	v_mfma_f32_16x16x32_bf16 v[62:65], v[194:197], v[134:137], v[62:65]
	v_mfma_f32_16x16x32_bf16 v[58:61], v[198:201], v[138:141], v[58:61]
	v_mfma_f32_16x16x32_bf16 v[62:65], v[198:201], v[142:145], v[62:65]
	ds_read_b64_tr_b16 v[194:195], v244 offset:17920
	ds_read_b64_tr_b16 v[196:197], v244 offset:22016
	ds_read_b64_tr_b16 v[198:199], v244 offset:26112
	ds_read_b64_tr_b16 v[200:201], v244 offset:30208
	s_waitcnt lgkmcnt(8)
	v_mfma_f32_16x16x32_bf16 v[34:37], v[146:149], v[130:133], v[34:37]
	v_mfma_f32_16x16x32_bf16 v[38:41], v[146:149], v[134:137], v[38:41]
	v_mfma_f32_16x16x32_bf16 v[34:37], v[150:153], v[138:141], v[34:37]
	v_mfma_f32_16x16x32_bf16 v[38:41], v[150:153], v[142:145], v[38:41]
	ds_read_b64_tr_b16 v[146:147], v244 offset:18176
	ds_read_b64_tr_b16 v[148:149], v244 offset:22272
	ds_read_b64_tr_b16 v[150:151], v244 offset:26368
	ds_read_b64_tr_b16 v[152:153], v244 offset:30464
	s_waitcnt lgkmcnt(8)
	v_mfma_f32_16x16x32_bf16 v[42:45], v[154:157], v[130:133], v[42:45]
	v_mfma_f32_16x16x32_bf16 v[46:49], v[154:157], v[134:137], v[46:49]
	v_mfma_f32_16x16x32_bf16 v[42:45], v[158:161], v[138:141], v[42:45]
	v_mfma_f32_16x16x32_bf16 v[46:49], v[158:161], v[142:145], v[46:49]
	s_waitcnt lgkmcnt(4)
	v_mfma_f32_16x16x32_bf16 v[18:21], v[194:197], v[130:133], v[18:21]
	v_mfma_f32_16x16x32_bf16 v[22:25], v[194:197], v[134:137], v[22:25]
	v_mfma_f32_16x16x32_bf16 v[18:21], v[198:201], v[138:141], v[18:21]
	v_mfma_f32_16x16x32_bf16 v[22:25], v[198:201], v[142:145], v[22:25]
	s_waitcnt lgkmcnt(0)
	v_mfma_f32_16x16x32_bf16 v[26:29], v[146:149], v[130:133], v[26:29]
	v_mfma_f32_16x16x32_bf16 v[30:33], v[146:149], v[134:137], v[30:33]
	v_mfma_f32_16x16x32_bf16 v[26:29], v[150:153], v[138:141], v[26:29]
	v_mfma_f32_16x16x32_bf16 v[30:33], v[150:153], v[142:145], v[30:33]
	s_waitcnt vmcnt(0)
	s_barrier
	s_xor_b32 s9, s25, 1
	s_lshl_b32 s9, s9, 14
	s_add_i32 s9, s9, 0x10000
	v_add_u32_e32 v230, s9, v232
	v_add_u32_e32 v247, s9, v233
	v_add_u32_e32 v228, s9, v246
	v_add_u32_e32 v245, s9, v249
	ds_read_b128 v[194:197], v230
	ds_read_b128 v[198:201], v230 offset:4096
	ds_read_b128 v[202:205], v230 offset:8192
	ds_read_b128 v[206:209], v230 offset:12288
	ds_read_b128 v[210:213], v247
	ds_read_b128 v[214:217], v247 offset:4096
	s_cmp_ge_u32 s13, s19
	s_cbranch_scc1 .Lat_x_nodma
	v_lshl_add_u64 v[130:131], v[220:221], 0, s[14:15]
	v_lshl_add_u64 v[132:133], v[222:223], 0, s[14:15]
	v_lshl_add_u64 v[134:135], v[224:225], 0, s[14:15]
	v_lshl_add_u64 v[136:137], v[226:227], 0, s[14:15]
	v_lshl_add_u64 v[138:139], v[134:135], 0, s[54:55]
	v_lshl_add_u64 v[134:135], v[134:135], 0, s[4:5]
	v_lshl_add_u64 v[140:141], v[136:137], 0, s[54:55]
	v_lshl_add_u64 v[136:137], v[136:137], 0, s[4:5]
	s_add_i32 s9, s22, s24
	s_add_i32 s8, s21, s100
	s_mov_b32 m0, s9
	s_nop 0
	global_load_lds_dwordx4 v[130:131], off
	s_add_i32 m0, s9, 0x2000
	s_nop 0
	global_load_lds_dwordx4 v[132:133], off
	s_mov_b32 m0, s8
	s_nop 0
	global_load_lds_dwordx4 v[138:139], off
	s_add_i32 m0, s8, 0x4000
	s_nop 0
	global_load_lds_dwordx4 v[134:135], off
	s_add_i32 m0, s8, 0x2000
	s_nop 0
	global_load_lds_dwordx4 v[140:141], off
	s_add_i32 m0, s8, 0x6000
	s_nop 0
	global_load_lds_dwordx4 v[136:137], off

; __device__ __forceinline__ void partialSM(f32x16& p0, f32x16& p1, float& m_reg, float& mn, float& alpha) {
;   constexpr float C = SCALE * 1.4426950408889634f;
;   float pmax = p0[0]; for (int r = 1; r < 16; ++r) pmax = fmaxf(pmax, p0[r]); for (int r = 0; r < 16; ++r) pmax = fmaxf(pmax, p1[r]);
;   { auto rr = __builtin_amdgcn_permlane32_swap(__float_as_uint(pmax), __float_as_uint(pmax), false, false);
;     pmax = fmaxf(__uint_as_float(rr[0]), __uint_as_float(rr[1])); }
;   if (__builtin_expect(__all(pmax - m_reg <= THR / SCALE), 1)) { mn = m_reg; alpha = 1.f; }
;   else { mn = fmaxf(m_reg, pmax); alpha = __builtin_amdgcn_exp2f((m_reg - mn) * C); m_reg = mn; }
;   float mnC = -mn * C;
;   for (int r = 0; r < 16; ++r) p0[r] = fmaf(p0[r], C, mnC); for (int r = 0; r < 16; ++r) p1[r] = fmaf(p1[r], C, mnC);
;   for (int r = 0; r < 16; ++r) p0[r] = __builtin_amdgcn_exp2f(p0[r]);
; }
; __device__ __forceinline__ void finishSM(f32x16& p0, f32x16& p1, float alpha, float& l_reg, bf16x8& pa0, bf16x8& pa1, bf16x8& pa2, bf16x8& pa3) {
;   for (int r = 0; r < 16; ++r) p1[r] = __builtin_amdgcn_exp2f(p1[r]);
;   float ps = 0; for (int r = 0; r < 16; ++r) ps += p0[r]; for (int r = 0; r < 16; ++r) ps += p1[r];
;   { auto rr = __builtin_amdgcn_permlane32_swap(__float_as_uint(ps), __float_as_uint(ps), false, false);
;     ps = __uint_as_float(rr[0]) + __uint_as_float(rr[1]); }
;   l_reg = l_reg * alpha + ps;
;     ...
;   PK4(p0, 0, pa0); PK4(p0, 8, pa1); PK4(p1, 0, pa2); PK4(p1, 8, pa3);
;     ...
; }
; __device__ __forceinline__ void qkt(f32x16& p0, f32x16& p1, const bf16_t* Ks, const bf16x8* qr, int r32, int hi) {
;   p0 = f32x16{}; p1 = f32x16{};
;   for (int d0 = 0; d0 < 8; ++d0) { int cb = (d0 * 16 + hi * 8) * 2;
;     bf16x8 b0 = *reinterpret_cast<const bf16x8*>((const char*)Ks + KSWZ(r32, cb));
;     bf16x8 b1 = *reinterpret_cast<const bf16x8*>((const char*)Ks + KSWZ(32 + r32, cb));
;     p0 = __builtin_amdgcn_mfma_f32_32x32x16_bf16(b0, qr[d0], p0, 0, 0, 0);
;     p1 = __builtin_amdgcn_mfma_f32_32x32x16_bf16(b1, qr[d0], p1, 0, 0, 0); }
; }
.Lat_y_nodma:
.Lat_y_qk:
	s_add_i32 s8, s13, -2
	s_and_b32 s25, s8, 1
	s_lshl_b32 s24, s25, 14
	s_add_i32 s8, s24, 0x10000
	v_add_u32_e32 v230, s8, v232
	v_add_u32_e32 v247, s8, v233
	v_add_u32_e32 v228, s8, v246
	v_add_u32_e32 v245, s8, v249
	s_setprio 1
	ds_read_b128 v[194:197], v230
	ds_read_b128 v[198:201], v230 offset:4096
	ds_read_b128 v[202:205], v230 offset:8192
	ds_read_b128 v[206:209], v230 offset:12288
	ds_read_b128 v[210:213], v247
	ds_read_b128 v[214:217], v247 offset:4096
	s_waitcnt lgkmcnt(5)
	v_mfma_f32_16x16x32_bf16 v[130:133], v[194:197], v[162:165], v[236:239]
	v_mfma_f32_16x16x32_bf16 v[134:137], v[194:197], v[178:181], v[240:243]
	ds_read_b128 v[194:197], v247 offset:8192
	s_waitcnt lgkmcnt(5)
	v_mfma_f32_16x16x32_bf16 v[138:141], v[198:201], v[162:165], v[236:239]
	v_mfma_f32_16x16x32_bf16 v[142:145], v[198:201], v[178:181], v[240:243]
	ds_read_b128 v[198:201], v247 offset:12288
	s_waitcnt lgkmcnt(5)
	v_mfma_f32_16x16x32_bf16 v[146:149], v[202:205], v[162:165], v[236:239]
	v_mfma_f32_16x16x32_bf16 v[150:153], v[202:205], v[178:181], v[240:243]
	ds_read_b128 v[202:205], v228
	s_waitcnt lgkmcnt(5)
	v_mfma_f32_16x16x32_bf16 v[154:157], v[206:209], v[162:165], v[236:239]
	v_mfma_f32_16x16x32_bf16 v[158:161], v[206:209], v[178:181], v[240:243]
	ds_read_b128 v[206:209], v228 offset:4096
	s_waitcnt lgkmcnt(5)
	v_mfma_f32_16x16x32_bf16 v[130:133], v[210:213], v[166:169], v[130:133]
	v_mfma_f32_16x16x32_bf16 v[134:137], v[210:213], v[182:185], v[134:137]
	ds_read_b128 v[210:213], v228 offset:8192
	s_waitcnt lgkmcnt(5)
	v_mfma_f32_16x16x32_bf16 v[138:141], v[214:217], v[166:169], v[138:141]
	v_mfma_f32_16x16x32_bf16 v[142:145], v[214:217], v[182:185], v[142:145]
	ds_read_b128 v[214:217], v228 offset:12288
	s_waitcnt lgkmcnt(5)
	v_mfma_f32_16x16x32_bf16 v[146:149], v[194:197], v[166:169], v[146:149]
	v_mfma_f32_16x16x32_bf16 v[150:153], v[194:197], v[182:185], v[150:153]
	ds_read_b128 v[194:197], v245
	s_waitcnt lgkmcnt(5)
	v_mfma_f32_16x16x32_bf16 v[154:157], v[198:201], v[166:169], v[154:157]
	v_mfma_f32_16x16x32_bf16 v[158:161], v[198:201], v[182:185], v[158:161]
	ds_read_b128 v[198:201], v245 offset:4096
	s_waitcnt lgkmcnt(5)
	v_mfma_f32_16x16x32_bf16 v[130:133], v[202:205], v[170:173], v[130:133]
	v_mfma_f32_16x16x32_bf16 v[134:137], v[202:205], v[186:189], v[134:137]
	ds_read_b128 v[202:205], v245 offset:8192
	s_waitcnt lgkmcnt(5)
	v_mfma_f32_16x16x32_bf16 v[138:141], v[206:209], v[170:173], v[138:141]
	v_mfma_f32_16x16x32_bf16 v[142:145], v[206:209], v[186:189], v[142:145]
	ds_read_b128 v[206:209], v245 offset:12288
	s_waitcnt lgkmcnt(5)
	v_mfma_f32_16x16x32_bf16 v[146:149], v[210:213], v[170:173], v[146:149]
	v_mfma_f32_16x16x32_bf16 v[150:153], v[210:213], v[186:189], v[150:153]
	s_waitcnt lgkmcnt(4)
	v_mfma_f32_16x16x32_bf16 v[154:157], v[214:217], v[170:173], v[154:157]
	v_mfma_f32_16x16x32_bf16 v[158:161], v[214:217], v[186:189], v[158:161]
	s_waitcnt lgkmcnt(3)
	v_mfma_f32_16x16x32_bf16 v[130:133], v[194:197], v[174:177], v[130:133]
	v_mfma_f32_16x16x32_bf16 v[134:137], v[194:197], v[190:193], v[134:137]
	s_waitcnt lgkmcnt(2)
	v_mfma_f32_16x16x32_bf16 v[138:141], v[198:201], v[174:177], v[138:141]
	v_mfma_f32_16x16x32_bf16 v[142:145], v[198:201], v[190:193], v[142:145]
	s_waitcnt lgkmcnt(1)
	v_mfma_f32_16x16x32_bf16 v[146:149], v[202:205], v[174:177], v[146:149]
	v_mfma_f32_16x16x32_bf16 v[150:153], v[202:205], v[190:193], v[150:153]
	s_waitcnt lgkmcnt(0)
	v_mfma_f32_16x16x32_bf16 v[154:157], v[206:209], v[174:177], v[154:157]
	v_mfma_f32_16x16x32_bf16 v[158:161], v[206:209], v[190:193], v[158:161]
	s_setprio 0
	s_nop 6
	v_max3_f32 v194, v130, v131, v132
	v_max3_f32 v194, v194, v133, v138
	v_max3_f32 v194, v194, v139, v140
	v_max3_f32 v194, v194, v141, v146
	v_max3_f32 v194, v194, v147, v148
	v_max3_f32 v194, v194, v149, v154
	v_max3_f32 v194, v194, v155, v156
	v_max_f32_e32 v194, v194, v157
	v_max3_f32 v195, v134, v135, v136
	v_max3_f32 v195, v195, v137, v142
	v_max3_f32 v195, v195, v143, v144
	v_max3_f32 v195, v195, v145, v150
	v_max3_f32 v195, v195, v151, v152
	v_max3_f32 v195, v195, v153, v158
	v_max3_f32 v195, v195, v159, v160
	v_max_f32_e32 v195, v195, v161
	v_mov_b32_e32 v196, v194
	v_mov_b32_e32 v197, v195
	s_nop 1
	v_permlane32_swap_b32_e32 v194, v196
	v_permlane32_swap_b32_e32 v195, v197
	v_max_f32_e32 v194, v194, v196
	v_max_f32_e32 v195, v195, v197
	v_mov_b32_e32 v196, v194
	v_mov_b32_e32 v197, v195
	s_nop 1
	v_permlane16_swap_b32_e32 v194, v196
	v_permlane16_swap_b32_e32 v195, v197
	v_max_f32_e32 v194, v194, v196
	v_max_f32_e32 v195, v195, v197
	v_max_f32_e32 v196, v194, v195
	v_cmp_nge_f32_e32 vcc, 0x4138aa3b, v196
	s_cbranch_vccnz .Lat_y_rare
	s_cmp_lg_u32 s13, 2
	s_cbranch_scc1 .Lat_y_noresc

; #define SBAR() __builtin_amdgcn_sched_barrier(0)
; __device__ __forceinline__ int crow(int r, int hi) { return (r & 3) + 8 * (r >> 2) + 4 * hi; }
; __device__ __forceinline__ int crow(int r, int hi) { return (r & 3) + 8 * (r >> 2) + 4 * hi; }
; __device__ __forceinline__ void partialSM(f32x16& p0, f32x16& p1, float& m_reg, float& mn, float& alpha) {
;     ...
;   for (int r = 0; r < 16; ++r) p0[r] = __builtin_amdgcn_exp2f(p0[r]);
; }
; __device__ __forceinline__ void finishSM(f32x16& p0, f32x16& p1, float alpha, float& l_reg, bf16x8& pa0, bf16x8& pa1, bf16x8& pa2, bf16x8& pa3) {
;   for (int r = 0; r < 16; ++r) p1[r] = __builtin_amdgcn_exp2f(p1[r]);
;   float ps = 0; for (int r = 0; r < 16; ++r) ps += p0[r]; for (int r = 0; r < 16; ++r) ps += p1[r];
;   { auto rr = __builtin_amdgcn_permlane32_swap(__float_as_uint(ps), __float_as_uint(ps), false, false);
;     ps = __uint_as_float(rr[0]) + __uint_as_float(rr[1]); }
;   l_reg = l_reg * alpha + ps;
;     ...
;   PK4(p0, 0, pa0); PK4(p0, 8, pa1); PK4(p1, 0, pa2); PK4(p1, 8, pa3);
; __device__ __forceinline__ void attn_body256(const bf16_t* __restrict__ Qb, const bf16_t* __restrict__ Kh, const bf16_t* __restrict__ Vh,
;                                              bf16_t* Ob, int seq, unsigned char* lds, float lam, int MODE, bf16_t* Ab, const float* wsub) {
;     ...
;   for (int j = 0; j < NT; ++j) {
;     const int b = j & 1;
;     f32x16 p0, p1; float mn, alpha; bf16x8 pa0, pa1, pa2, pa3;
;     SBAR(); qkt(p0, p1, (const bf16_t*)(lds + A2_KOFF + b * A2_KBUF), qr, r32, hi);
;     partialSM(p0, p1, m_reg, mn, alpha);
;     if (__any(alpha < 1.f)) { if (hi == 0) al_l[r32] = alpha; asm volatile("s_waitcnt lgkmcnt(0)" ::: "memory");
; #pragma unroll
;       for (int r = 0; r < 16; ++r) { const float a = al_l[crow(r, hi)];
; #pragma unroll
;         for (int d = 0; d < 8; ++d) o[d][r] *= a; } }
;     finishSM(p0, p1, alpha, l_reg, pa0, pa1, pa2, pa3); SBAR();
;     pv_all(o, vb0 + b * A2_VBUF, pa0, pa1, pa2, pa3);
;     asm volatile("s_waitcnt vmcnt(0)" ::: "memory"); __syncthreads();
;     if (j + 2 < NT) A2_DMA(j + 2, b);
.Lat_y_noresc:
	v_exp_f32_e32 v130, v130
	v_exp_f32_e32 v131, v131
	v_exp_f32_e32 v132, v132
	v_exp_f32_e32 v133, v133
	v_exp_f32_e32 v134, v134
	v_exp_f32_e32 v135, v135
	v_exp_f32_e32 v136, v136
	v_exp_f32_e32 v137, v137
	v_exp_f32_e32 v138, v138
	v_exp_f32_e32 v139, v139
	v_exp_f32_e32 v140, v140
	v_exp_f32_e32 v141, v141
	v_exp_f32_e32 v142, v142
	v_exp_f32_e32 v143, v143
	v_exp_f32_e32 v144, v144
	v_exp_f32_e32 v145, v145
	v_exp_f32_e32 v146, v146
	v_exp_f32_e32 v147, v147
	v_exp_f32_e32 v148, v148
	v_exp_f32_e32 v149, v149
	v_exp_f32_e32 v150, v150
	v_exp_f32_e32 v151, v151
	v_exp_f32_e32 v152, v152
	v_exp_f32_e32 v153, v153
	v_exp_f32_e32 v154, v154
	v_exp_f32_e32 v155, v155
	v_exp_f32_e32 v156, v156
	v_exp_f32_e32 v157, v157
	v_exp_f32_e32 v158, v158
	v_exp_f32_e32 v159, v159
	v_exp_f32_e32 v160, v160
	v_exp_f32_e32 v161, v161
	v_add_f32_e32 v194, v130, v131
	v_add_f32_e32 v194, v194, v132
	v_add_f32_e32 v194, v194, v133
	v_add_f32_e32 v194, v194, v138
	v_add_f32_e32 v194, v194, v139
	v_add_f32_e32 v194, v194, v140
	v_add_f32_e32 v194, v194, v141
	v_add_f32_e32 v194, v194, v146
	v_add_f32_e32 v194, v194, v147
	v_add_f32_e32 v194, v194, v148
	v_add_f32_e32 v194, v194, v149
	v_add_f32_e32 v194, v194, v154
	v_add_f32_e32 v194, v194, v155
	v_add_f32_e32 v194, v194, v156
	v_add_f32_e32 v194, v194, v157
	v_add_f32_e32 v195, v134, v135
	v_add_f32_e32 v195, v195, v136
	v_add_f32_e32 v195, v195, v137
	v_add_f32_e32 v195, v195, v142
	v_add_f32_e32 v195, v195, v143
	v_add_f32_e32 v195, v195, v144
	v_add_f32_e32 v195, v195, v145
	v_add_f32_e32 v195, v195, v150
	v_add_f32_e32 v195, v195, v151
	v_add_f32_e32 v195, v195, v152
	v_add_f32_e32 v195, v195, v153
	v_add_f32_e32 v195, v195, v158
	v_add_f32_e32 v195, v195, v159
	v_add_f32_e32 v195, v195, v160
	v_add_f32_e32 v195, v195, v161
	v_add_f32_e32 v250, v250, v194
	v_add_f32_e32 v234, v234, v195
	v_cvt_pk_bf16_f32 v130, v130, v131
	v_cvt_pk_bf16_f32 v131, v132, v133
	v_cvt_pk_bf16_f32 v132, v138, v139
	v_cvt_pk_bf16_f32 v133, v140, v141
	v_cvt_pk_bf16_f32 v134, v134, v135
	v_cvt_pk_bf16_f32 v135, v136, v137
	v_cvt_pk_bf16_f32 v136, v142, v143
	v_cvt_pk_bf16_f32 v137, v144, v145
	v_cvt_pk_bf16_f32 v138, v146, v147
	v_cvt_pk_bf16_f32 v139, v148, v149
	v_cvt_pk_bf16_f32 v140, v154, v155
	v_cvt_pk_bf16_f32 v141, v156, v157
	v_cvt_pk_bf16_f32 v142, v150, v151
	v_cvt_pk_bf16_f32 v143, v152, v153
	v_cvt_pk_bf16_f32 v144, v158, v159
	v_cvt_pk_bf16_f32 v145, v160, v161
	v_add_u32_e32 v244, s98, v248
	ds_read_b64_tr_b16 v[146:147], v244
	ds_read_b64_tr_b16 v[148:149], v244 offset:4096
	ds_read_b64_tr_b16 v[150:151], v244 offset:8192
	ds_read_b64_tr_b16 v[152:153], v244 offset:12288
	ds_read_b64_tr_b16 v[154:155], v244 offset:256
	ds_read_b64_tr_b16 v[156:157], v244 offset:4352
	ds_read_b64_tr_b16 v[158:159], v244 offset:8448
	ds_read_b64_tr_b16 v[160:161], v244 offset:12544
	ds_read_b64_tr_b16 v[194:195], v244 offset:512
	ds_read_b64_tr_b16 v[196:197], v244 offset:4608
	ds_read_b64_tr_b16 v[198:199], v244 offset:8704
	ds_read_b64_tr_b16 v[200:201], v244 offset:12800
	s_waitcnt vmcnt(0)
	s_barrier
	s_mov_b32 s101, s98
	s_mov_b32 s98, s99
	s_mov_b32 s99, s100
	s_mov_b32 s100, s101
	s_add_u32 s14, s14, 0x40000
	s_addc_u32 s15, s15, 0
	s_add_i32 s13, s13, 1
	s_cmp_eq_u32 s23, s14
	s_cbranch_scc0 .Lat_y_top
	s_waitcnt lgkmcnt(8)
	v_mfma_f32_16x16x32_bf16 v[2:5], v[146:149], v[130:133], v[2:5]
	v_mfma_f32_16x16x32_bf16 v[6:9], v[146:149], v[134:137], v[6:9]
	v_mfma_f32_16x16x32_bf16 v[2:5], v[150:153], v[138:141], v[2:5]
	v_mfma_f32_16x16x32_bf16 v[6:9], v[150:153], v[142:145], v[6:9]
	ds_read_b64_tr_b16 v[146:147], v244 offset:768
	ds_read_b64_tr_b16 v[148:149], v244 offset:4864
	ds_read_b64_tr_b16 v[150:151], v244 offset:8960
	ds_read_b64_tr_b16 v[152:153], v244 offset:13056
	s_waitcnt lgkmcnt(8)
	v_mfma_f32_16x16x32_bf16 v[10:13], v[154:157], v[130:133], v[10:13]
	v_mfma_f32_16x16x32_bf16 v[14:17], v[154:157], v[134:137], v[14:17]
	v_mfma_f32_16x16x32_bf16 v[10:13], v[158:161], v[138:141], v[10:13]
	v_mfma_f32_16x16x32_bf16 v[14:17], v[158:161], v[142:145], v[14:17]
	ds_read_b64_tr_b16 v[154:155], v244 offset:1024
	ds_read_b64_tr_b16 v[156:157], v244 offset:5120
	ds_read_b64_tr_b16 v[158:159], v244 offset:9216
	ds_read_b64_tr_b16 v[160:161], v244 offset:13312
	s_waitcnt lgkmcnt(8)
	v_mfma_f32_16x16x32_bf16 v[114:117], v[194:197], v[130:133], v[114:117]
	v_mfma_f32_16x16x32_bf16 v[118:121], v[194:197], v[134:137], v[118:121]
	v_mfma_f32_16x16x32_bf16 v[114:117], v[198:201], v[138:141], v[114:117]
	v_mfma_f32_16x16x32_bf16 v[118:121], v[198:201], v[142:145], v[118:121]
	ds_read_b64_tr_b16 v[194:195], v244 offset:1280
	ds_read_b64_tr_b16 v[196:197], v244 offset:5376
	ds_read_b64_tr_b16 v[198:199], v244 offset:9472
	ds_read_b64_tr_b16 v[200:201], v244 offset:13568
	s_waitcnt lgkmcnt(8)
	v_mfma_f32_16x16x32_bf16 v[122:125], v[146:149], v[130:133], v[122:125]
	v_mfma_f32_16x16x32_bf16 v[126:129], v[146:149], v[134:137], v[126:129]
	v_mfma_f32_16x16x32_bf16 v[122:125], v[150:153], v[138:141], v[122:125]
	v_mfma_f32_16x16x32_bf16 v[126:129], v[150:153], v[142:145], v[126:129]
	ds_read_b64_tr_b16 v[146:147], v244 offset:1536
	ds_read_b64_tr_b16 v[148:149], v244 offset:5632
	ds_read_b64_tr_b16 v[150:151], v244 offset:9728
	ds_read_b64_tr_b16 v[152:153], v244 offset:13824
	s_waitcnt lgkmcnt(8)
; #define SBAR() __builtin_amdgcn_sched_barrier(0)
; #define PV_STEP(B) do { pv_reads<(B) + 1>(fn, vb); asm volatile("s_waitcnt lgkmcnt(8)" ::: "memory"); SBAR(); pv_mma(o[B], fc, pa0, pa1, pa2, pa3); SBAR(); fc = fn; } while (0)
; __device__ __forceinline__ void pv_all(f32x16* o, int vb, bf16x8 pa0, bf16x8 pa1, bf16x8 pa2, bf16x8 pa3) {
;   VFrag fc, fn;
;   pv_reads<0>(fc, vb);
;   PV_STEP(0); PV_STEP(1); PV_STEP(2); PV_STEP(3); PV_STEP(4); PV_STEP(5); PV_STEP(6);
;   asm volatile("s_waitcnt lgkmcnt(0)" ::: "memory"); SBAR(); pv_mma(o[7], fc, pa0, pa1, pa2, pa3);
; }
	v_mfma_f32_16x16x32_bf16 v[98:101], v[154:157], v[130:133], v[98:101]
	v_mfma_f32_16x16x32_bf16 v[102:105], v[154:157], v[134:137], v[102:105]
	v_mfma_f32_16x16x32_bf16 v[98:101], v[158:161], v[138:141], v[98:101]
	v_mfma_f32_16x16x32_bf16 v[102:105], v[158:161], v[142:145], v[102:105]
	ds_read_b64_tr_b16 v[154:155], v244 offset:1792
	ds_read_b64_tr_b16 v[156:157], v244 offset:5888
	ds_read_b64_tr_b16 v[158:159], v244 offset:9984
	ds_read_b64_tr_b16 v[160:161], v244 offset:14080
	s_waitcnt lgkmcnt(8)
	v_mfma_f32_16x16x32_bf16 v[106:109], v[194:197], v[130:133], v[106:109]
	v_mfma_f32_16x16x32_bf16 v[110:113], v[194:197], v[134:137], v[110:113]
	v_mfma_f32_16x16x32_bf16 v[106:109], v[198:201], v[138:141], v[106:109]
	v_mfma_f32_16x16x32_bf16 v[110:113], v[198:201], v[142:145], v[110:113]
	ds_read_b64_tr_b16 v[194:195], v244 offset:16384
	ds_read_b64_tr_b16 v[196:197], v244 offset:20480
	ds_read_b64_tr_b16 v[198:199], v244 offset:24576
	ds_read_b64_tr_b16 v[200:201], v244 offset:28672
	s_waitcnt lgkmcnt(8)
	v_mfma_f32_16x16x32_bf16 v[82:85], v[146:149], v[130:133], v[82:85]
	v_mfma_f32_16x16x32_bf16 v[86:89], v[146:149], v[134:137], v[86:89]
	v_mfma_f32_16x16x32_bf16 v[82:85], v[150:153], v[138:141], v[82:85]
	v_mfma_f32_16x16x32_bf16 v[86:89], v[150:153], v[142:145], v[86:89]
	ds_read_b64_tr_b16 v[146:147], v244 offset:16640
	ds_read_b64_tr_b16 v[148:149], v244 offset:20736
	ds_read_b64_tr_b16 v[150:151], v244 offset:24832
	ds_read_b64_tr_b16 v[152:153], v244 offset:28928
	s_waitcnt lgkmcnt(8)
	v_mfma_f32_16x16x32_bf16 v[90:93], v[154:157], v[130:133], v[90:93]
	v_mfma_f32_16x16x32_bf16 v[94:97], v[154:157], v[134:137], v[94:97]
	v_mfma_f32_16x16x32_bf16 v[90:93], v[158:161], v[138:141], v[90:93]
	v_mfma_f32_16x16x32_bf16 v[94:97], v[158:161], v[142:145], v[94:97]
	ds_read_b64_tr_b16 v[154:155], v244 offset:16896
	ds_read_b64_tr_b16 v[156:157], v244 offset:20992
	ds_read_b64_tr_b16 v[158:159], v244 offset:25088
	ds_read_b64_tr_b16 v[160:161], v244 offset:29184
	s_waitcnt lgkmcnt(8)
	v_mfma_f32_16x16x32_bf16 v[66:69], v[194:197], v[130:133], v[66:69]
	v_mfma_f32_16x16x32_bf16 v[70:73], v[194:197], v[134:137], v[70:73]
	v_mfma_f32_16x16x32_bf16 v[66:69], v[198:201], v[138:141], v[66:69]
	v_mfma_f32_16x16x32_bf16 v[70:73], v[198:201], v[142:145], v[70:73]
	ds_read_b64_tr_b16 v[194:195], v244 offset:17152
	ds_read_b64_tr_b16 v[196:197], v244 offset:21248
	ds_read_b64_tr_b16 v[198:199], v244 offset:25344
	ds_read_b64_tr_b16 v[200:201], v244 offset:29440
	s_waitcnt lgkmcnt(8)
	v_mfma_f32_16x16x32_bf16 v[74:77], v[146:149], v[130:133], v[74:77]
	v_mfma_f32_16x16x32_bf16 v[78:81], v[146:149], v[134:137], v[78:81]
	v_mfma_f32_16x16x32_bf16 v[74:77], v[150:153], v[138:141], v[74:77]
	v_mfma_f32_16x16x32_bf16 v[78:81], v[150:153], v[142:145], v[78:81]
	ds_read_b64_tr_b16 v[146:147], v244 offset:17408
	ds_read_b64_tr_b16 v[148:149], v244 offset:21504
	ds_read_b64_tr_b16 v[150:151], v244 offset:25600
	ds_read_b64_tr_b16 v[152:153], v244 offset:29696
	s_waitcnt lgkmcnt(8)
	v_mfma_f32_16x16x32_bf16 v[50:53], v[154:157], v[130:133], v[50:53]
	v_mfma_f32_16x16x32_bf16 v[54:57], v[154:157], v[134:137], v[54:57]
	v_mfma_f32_16x16x32_bf16 v[50:53], v[158:161], v[138:141], v[50:53]
	v_mfma_f32_16x16x32_bf16 v[54:57], v[158:161], v[142:145], v[54:57]
	ds_read_b64_tr_b16 v[154:155], v244 offset:17664
	ds_read_b64_tr_b16 v[156:157], v244 offset:21760
	ds_read_b64_tr_b16 v[158:159], v244 offset:25856
	ds_read_b64_tr_b16 v[160:161], v244 offset:29952
	s_waitcnt lgkmcnt(8)
	v_mfma_f32_16x16x32_bf16 v[58:61], v[194:197], v[130:133], v[58:61]
	v_mfma_f32_16x16x32_bf16 v[62:65], v[194:197], v[134:137], v[62:65]
	v_mfma_f32_16x16x32_bf16 v[58:61], v[198:201], v[138:141], v[58:61]
	v_mfma_f32_16x16x32_bf16 v[62:65], v[198:201], v[142:145], v[62:65]
	ds_read_b64_tr_b16 v[194:195], v244 offset:17920
	ds_read_b64_tr_b16 v[196:197], v244 offset:22016
	ds_read_b64_tr_b16 v[198:199], v244 offset:26112
	ds_read_b64_tr_b16 v[200:201], v244 offset:30208
	s_waitcnt lgkmcnt(8)
	v_mfma_f32_16x16x32_bf16 v[34:37], v[146:149], v[130:133], v[34:37]
	v_mfma_f32_16x16x32_bf16 v[38:41], v[146:149], v[134:137], v[38:41]
	v_mfma_f32_16x16x32_bf16 v[34:37], v[150:153], v[138:141], v[34:37]
	v_mfma_f32_16x16x32_bf16 v[38:41], v[150:153], v[142:145], v[38:41]
	ds_read_b64_tr_b16 v[146:147], v244 offset:18176
	ds_read_b64_tr_b16 v[148:149], v244 offset:22272
	ds_read_b64_tr_b16 v[150:151], v244 offset:26368
	ds_read_b64_tr_b16 v[152:153], v244 offset:30464
	s_waitcnt lgkmcnt(8)
	v_mfma_f32_16x16x32_bf16 v[42:45], v[154:157], v[130:133], v[42:45]
	v_mfma_f32_16x16x32_bf16 v[46:49], v[154:157], v[134:137], v[46:49]
	v_mfma_f32_16x16x32_bf16 v[42:45], v[158:161], v[138:141], v[42:45]
	v_mfma_f32_16x16x32_bf16 v[46:49], v[158:161], v[142:145], v[46:49]
	s_waitcnt lgkmcnt(4)
	v_mfma_f32_16x16x32_bf16 v[18:21], v[194:197], v[130:133], v[18:21]
	v_mfma_f32_16x16x32_bf16 v[22:25], v[194:197], v[134:137], v[22:25]
	v_mfma_f32_16x16x32_bf16 v[18:21], v[198:201], v[138:141], v[18:21]
	v_mfma_f32_16x16x32_bf16 v[22:25], v[198:201], v[142:145], v[22:25]
	s_waitcnt lgkmcnt(0)
	v_mfma_f32_16x16x32_bf16 v[26:29], v[146:149], v[130:133], v[26:29]
	v_mfma_f32_16x16x32_bf16 v[30:33], v[146:149], v[134:137], v[30:33]
	v_mfma_f32_16x16x32_bf16 v[26:29], v[150:153], v[138:141], v[26:29]
	v_mfma_f32_16x16x32_bf16 v[30:33], v[150:153], v[142:145], v[30:33]
